# WIN: z column tiles that only M3 reads (q, silu gate, lru gate) stored write-through; first-trip waits of later WIN units relaxed for the 16 epilogue stores
# baseline (speedup 1.0000x reference)
; #define PG8_STAGE(bufoff, gbase, voff) do { _Pragma("unroll") for (int _i = 0; _i < 2; ++_i) \
;         __builtin_amdgcn_global_load_lds((const unsigned*)((const char*)(gbase) + (voff)[_i]), (PG8_LAS unsigned*)(lds + (bufoff) + ldsw + _i * 8192), 16, 0, 0); } while (0)
; #define PG8_LDA(dst, b, h) do { _Pragma("unroll") for (int m = 0; m < 4; ++m) _Pragma("unroll") for (int k = 0; k < 2; ++k) dst[m][k] = *(const PG8_LAS bf16x8*)(lds + PG8_SA(b, h) + aoff + m * 2048 + k * 1024); } while (0)
; #define PG8_LDB(dst, b, h) do { _Pragma("unroll") for (int n = 0; n < 2; ++n) _Pragma("unroll") for (int k = 0; k < 2; ++k) dst[n][k] = *(const PG8_LAS bf16x8*)(lds + PG8_SB(b, h) + boff + n * 2048 + k * 1024); } while (0)
; #define PG8_MMA(ai, bj, At, Bt) do { __builtin_amdgcn_s_setprio(1); _Pragma("unroll") for (int m = 0; m < 4; ++m) _Pragma("unroll") for (int n = 0; n < 2; ++n) _Pragma("unroll") for (int k = 0; k < 2; ++k) \
;         acc[ai][bj][m][n] = __builtin_amdgcn_mfma_f32_16x16x32_bf16(Bt[n][k], At[m][k], acc[ai][bj][m][n], 0, 0, 0); __builtin_amdgcn_s_setprio(0); } while (0)
; #define PG8_WAIT_V(n) asm volatile("s_waitcnt vmcnt(" #n ")" ::: "memory")
; #define PG8_WAIT_L(n) asm volatile("s_waitcnt lgkmcnt(" #n ")" ::: "memory")
; #define PG8_BAR __builtin_amdgcn_s_barrier()
; #define PG8_SCHED __builtin_amdgcn_sched_barrier(0)
; template <class Epi, class Sched, bool ALIGN_EPI = false, bool SP2 = false>
; __device__ __forceinline__ void gemm_phase(PG8_LAS unsigned char* lds, const Gemm g, const Sched& S, const Epi& E) {
;     ...
;             PG8_LDB(B0, 0, 0); PG8_LDB(B1, 0, 1); PG8_SCHED; PG8_LDA(At, 0, 0); PG8_STAGE(PG8_SA(1, 1), a1 + hstep, voffA);
;             PG8_WAIT_V(8); PG8_WAIT_L(0); PG8_BAR; PG8_MMA(0, 0, At, B0); PG8_MMA(0, 1, At, B1); PG8_BAR; PG8_SCHED;
;             PG8_LDA(At, 0, 1); PG8_STAGE(PG8_SB(0, 0), b2, voffB); PG8_STAGE(PG8_SB(0, 1), b2 + hstep, voffB); PG8_STAGE(PG8_SA(0, 0), a2, voffA);
;             PG8_WAIT_V(8); PG8_WAIT_L(0); PG8_BAR; PG8_MMA(1, 0, At, B0); PG8_MMA(1, 1, At, B1); PG8_BAR; PG8_SCHED;
.LBB0_244:
	s_add_u32 s6, s4, 0xfffc0080
	s_addc_u32 s7, s5, -1
	s_and_b64 s[0:1], s[0:1], exec
	s_cselect_b32 s7, s38, s7
	s_cselect_b32 s6, s39, s6
	s_cselect_b32 s1, s49, s57
	s_cselect_b32 s0, s55, s56
	s_cmp_eq_u32 s58, -2
	s_cselect_b32 vcc_lo, 1, 0
	s_cmp_gt_u32 s34, 1
	s_cselect_b32 vcc_lo, vcc_lo, 0
	s_add_i32 s59, 0, 0x10000
	v_add_u32_e32 v144, s59, v197
	s_add_i32 s62, 0, 0x14000
	ds_read_b128 v[132:135], v144
	ds_read_b128 v[136:139], v144 offset:1024
	ds_read_b128 v[140:143], v144 offset:2048
	ds_read_b128 v[202:205], v144 offset:3072
	v_add_u32_e32 v144, s62, v197
	ds_read_b128 v[206:209], v144
	ds_read_b128 v[210:213], v144 offset:1024
	ds_read_b128 v[214:217], v144 offset:2048
	ds_read_b128 v[218:221], v144 offset:3072
	v_lshl_add_u64 v[172:173], s[4:5], 0, v[166:167]
	s_add_i32 m0, s25, 0xc000
	ds_read_b128 v[222:225], v199
	ds_read_b128 v[226:229], v199 offset:1024
	ds_read_b128 v[230:233], v199 offset:2048
	ds_read_b128 v[234:237], v199 offset:3072
	ds_read_b128 v[238:241], v199 offset:4096
	ds_read_b128 v[242:245], v199 offset:5120
	ds_read_b128 v[246:249], v199 offset:6144
	ds_read_b128 v[180:183], v199 offset:7168
	global_load_lds_dwordx4 v[172:173], off
	v_lshl_add_u64 v[172:173], s[4:5], 0, v[168:169]
	s_add_i32 m0, s25, 0xe000
	s_nop 0
	global_load_lds_dwordx4 v[172:173], off
	s_waitcnt vmcnt(24)
	s_cmp_lg_u32 vcc_lo, 0
	s_cbranch_scc1 .Lwin_relaxed0
	s_waitcnt vmcnt(8)
.Lwin_relaxed0:
	s_waitcnt lgkmcnt(0)
	.p2alignl 3, 3212836864
	s_setprio 1
	s_barrier
	v_mfma_f32_16x16x32_bf16 v[124:127], v[132:135], v[222:225], v[124:127]
	v_mfma_f32_16x16x32_bf16 v[120:123], v[140:143], v[222:225], v[120:123]
	v_mfma_f32_16x16x32_bf16 v[108:111], v[132:135], v[230:233], v[108:111]
	v_mfma_f32_16x16x32_bf16 v[104:107], v[140:143], v[230:233], v[104:107]
	v_mfma_f32_16x16x32_bf16 v[92:95], v[132:135], v[238:241], v[92:95]
	v_mfma_f32_16x16x32_bf16 v[88:91], v[140:143], v[238:241], v[88:91]
	v_mfma_f32_16x16x32_bf16 v[76:79], v[132:135], v[246:249], v[76:79]
	v_mfma_f32_16x16x32_bf16 v[72:75], v[140:143], v[246:249], v[72:75]
	v_mfma_f32_16x16x32_bf16 v[124:127], v[136:139], v[226:229], v[124:127]
	v_mfma_f32_16x16x32_bf16 v[120:123], v[202:205], v[226:229], v[120:123]
	v_mfma_f32_16x16x32_bf16 v[108:111], v[136:139], v[234:237], v[108:111]
	v_mfma_f32_16x16x32_bf16 v[104:107], v[202:205], v[234:237], v[104:107]
	v_mfma_f32_16x16x32_bf16 v[92:95], v[136:139], v[242:245], v[92:95]
	v_mfma_f32_16x16x32_bf16 v[88:91], v[202:205], v[242:245], v[88:91]
	v_mfma_f32_16x16x32_bf16 v[76:79], v[136:139], v[180:183], v[76:79]
	v_mfma_f32_16x16x32_bf16 v[72:75], v[202:205], v[180:183], v[72:75]
	s_setprio 0
	s_setprio 1
	v_mfma_f32_16x16x32_bf16 v[116:119], v[206:209], v[222:225], v[116:119]
	v_mfma_f32_16x16x32_bf16 v[112:115], v[214:217], v[222:225], v[112:115]
	v_mfma_f32_16x16x32_bf16 v[100:103], v[206:209], v[230:233], v[100:103]
	v_mfma_f32_16x16x32_bf16 v[96:99], v[214:217], v[230:233], v[96:99]
	v_mfma_f32_16x16x32_bf16 v[84:87], v[206:209], v[238:241], v[84:87]
	v_mfma_f32_16x16x32_bf16 v[80:83], v[214:217], v[238:241], v[80:83]
	v_mfma_f32_16x16x32_bf16 v[68:71], v[206:209], v[246:249], v[68:71]
	v_mfma_f32_16x16x32_bf16 v[64:67], v[214:217], v[246:249], v[64:67]
	v_mfma_f32_16x16x32_bf16 v[116:119], v[210:213], v[226:229], v[116:119]
	v_mfma_f32_16x16x32_bf16 v[112:115], v[218:221], v[226:229], v[112:115]
	v_mfma_f32_16x16x32_bf16 v[100:103], v[210:213], v[234:237], v[100:103]
	v_mfma_f32_16x16x32_bf16 v[96:99], v[218:221], v[234:237], v[96:99]
	v_mfma_f32_16x16x32_bf16 v[84:87], v[210:213], v[242:245], v[84:87]
	v_mfma_f32_16x16x32_bf16 v[80:83], v[218:221], v[242:245], v[80:83]
	v_mfma_f32_16x16x32_bf16 v[68:71], v[210:213], v[180:183], v[68:71]
	v_mfma_f32_16x16x32_bf16 v[64:67], v[218:221], v[180:183], v[64:67]
	s_barrier
	s_setprio 0
	s_add_i32 s59, s59, s24
	v_lshl_add_u64 v[172:173], s[0:1], 0, v[154:155]
	s_mov_b32 m0, s59
	ds_read_b128 v[180:183], v199 offset:16384
	ds_read_b128 v[222:225], v199 offset:17408
	ds_read_b128 v[226:229], v199 offset:18432
	ds_read_b128 v[230:233], v199 offset:19456
	ds_read_b128 v[234:237], v199 offset:20480
	ds_read_b128 v[238:241], v199 offset:21504
	ds_read_b128 v[242:245], v199 offset:22528
	ds_read_b128 v[246:249], v199 offset:23552
	global_load_lds_dwordx4 v[172:173], off
	s_add_i32 m0, s59, 0x2000
	s_add_u32 s60, s0, 0x40000
	v_lshl_add_u64 v[184:185], s[0:1], 0, v[150:151]
	s_addc_u32 s61, s1, 0
	s_add_i32 s59, s62, s24
	global_load_lds_dwordx4 v[184:185], off
	v_lshl_add_u64 v[186:187], s[60:61], 0, v[154:155]
	s_mov_b32 m0, s59
	v_lshl_add_u64 v[188:189], s[6:7], 0, v[152:153]
	global_load_lds_dwordx4 v[186:187], off
	v_lshl_add_u64 v[186:187], s[60:61], 0, v[150:151]
	s_add_i32 m0, s59, 0x2000
	s_nop 0
	global_load_lds_dwordx4 v[186:187], off
	v_lshl_add_u64 v[186:187], s[6:7], 0, v[156:157]
	s_mov_b32 m0, s25
	s_nop 0
	global_load_lds_dwordx4 v[186:187], off
	s_mov_b32 m0, s26
	s_nop 0
	global_load_lds_dwordx4 v[188:189], off
	s_waitcnt vmcnt(24)
	s_cmp_lg_u32 vcc_lo, 0
	s_cbranch_scc1 .Lwin_relaxed1
	s_waitcnt vmcnt(8)
; #define PG8_STAGE(bufoff, gbase, voff) do { _Pragma("unroll") for (int _i = 0; _i < 2; ++_i) \
;         __builtin_amdgcn_global_load_lds((const unsigned*)((const char*)(gbase) + (voff)[_i]), (PG8_LAS unsigned*)(lds + (bufoff) + ldsw + _i * 8192), 16, 0, 0); } while (0)
; #define PG8_LDA(dst, b, h) do { _Pragma("unroll") for (int m = 0; m < 4; ++m) _Pragma("unroll") for (int k = 0; k < 2; ++k) dst[m][k] = *(const PG8_LAS bf16x8*)(lds + PG8_SA(b, h) + aoff + m * 2048 + k * 1024); } while (0)
; #define PG8_LDB(dst, b, h) do { _Pragma("unroll") for (int n = 0; n < 2; ++n) _Pragma("unroll") for (int k = 0; k < 2; ++k) dst[n][k] = *(const PG8_LAS bf16x8*)(lds + PG8_SB(b, h) + boff + n * 2048 + k * 1024); } while (0)
; #define PG8_MMA(ai, bj, At, Bt) do { __builtin_amdgcn_s_setprio(1); _Pragma("unroll") for (int m = 0; m < 4; ++m) _Pragma("unroll") for (int n = 0; n < 2; ++n) _Pragma("unroll") for (int k = 0; k < 2; ++k) \
;         acc[ai][bj][m][n] = __builtin_amdgcn_mfma_f32_16x16x32_bf16(Bt[n][k], At[m][k], acc[ai][bj][m][n], 0, 0, 0); __builtin_amdgcn_s_setprio(0); } while (0)
; #define PG8_WAIT_V(n) asm volatile("s_waitcnt vmcnt(" #n ")" ::: "memory")
; #define PG8_WAIT_L(n) asm volatile("s_waitcnt lgkmcnt(" #n ")" ::: "memory")
; #define PG8_BAR __builtin_amdgcn_s_barrier()
; #define PG8_SCHED __builtin_amdgcn_sched_barrier(0)
; template <class Epi, class Sched, bool ALIGN_EPI = false, bool SP2 = false>
; __device__ __forceinline__ void gemm_phase(PG8_LAS unsigned char* lds, const Gemm g, const Sched& S, const Epi& E) {
;     ...
;             PG8_WAIT_V(8); PG8_WAIT_L(0); PG8_BAR; PG8_MMA(1, 0, At, B0); PG8_MMA(1, 1, At, B1); PG8_BAR; PG8_SCHED;
;             PG8_LDB(B0, 1, 0); PG8_LDB(B1, 1, 1); PG8_SCHED; PG8_LDA(At, 1, 0); PG8_STAGE(PG8_SA(0, 1), a2 + hstep, voffA);
;             PG8_WAIT_V(8); PG8_WAIT_L(0); PG8_BAR; PG8_MMA(0, 0, At, B0); PG8_MMA(0, 1, At, B1); PG8_BAR; PG8_SCHED;
;             PG8_LDA(At, 1, 1); PG8_STAGE(PG8_SB(1, 0), b3, voffB); PG8_STAGE(PG8_SB(1, 1), b3 + hstep, voffB); PG8_STAGE(PG8_SA(1, 0), a3, voffA);
.Lwin_relaxed1:
	s_waitcnt lgkmcnt(0)
	.p2alignl 3, 3212836864
	s_setprio 1
	s_barrier
	v_mfma_f32_16x16x32_bf16 v[60:63], v[132:135], v[180:183], v[60:63]
	v_mfma_f32_16x16x32_bf16 v[56:59], v[140:143], v[180:183], v[56:59]
	v_mfma_f32_16x16x32_bf16 v[44:47], v[132:135], v[226:229], v[44:47]
	v_mfma_f32_16x16x32_bf16 v[40:43], v[140:143], v[226:229], v[40:43]
	v_mfma_f32_16x16x32_bf16 v[28:31], v[132:135], v[234:237], v[28:31]
	v_mfma_f32_16x16x32_bf16 v[24:27], v[140:143], v[234:237], v[24:27]
	v_mfma_f32_16x16x32_bf16 v[12:15], v[132:135], v[242:245], v[12:15]
	v_mfma_f32_16x16x32_bf16 v[8:11], v[140:143], v[242:245], v[8:11]
	v_mfma_f32_16x16x32_bf16 v[60:63], v[136:139], v[222:225], v[60:63]
	v_mfma_f32_16x16x32_bf16 v[56:59], v[202:205], v[222:225], v[56:59]
	v_mfma_f32_16x16x32_bf16 v[44:47], v[136:139], v[230:233], v[44:47]
	v_mfma_f32_16x16x32_bf16 v[40:43], v[202:205], v[230:233], v[40:43]
	v_mfma_f32_16x16x32_bf16 v[28:31], v[136:139], v[238:241], v[28:31]
	v_mfma_f32_16x16x32_bf16 v[24:27], v[202:205], v[238:241], v[24:27]
	v_mfma_f32_16x16x32_bf16 v[12:15], v[136:139], v[246:249], v[12:15]
	v_mfma_f32_16x16x32_bf16 v[8:11], v[202:205], v[246:249], v[8:11]
	s_setprio 0
	s_setprio 1
	v_mfma_f32_16x16x32_bf16 v[52:55], v[206:209], v[180:183], v[52:55]
	v_mfma_f32_16x16x32_bf16 v[48:51], v[214:217], v[180:183], v[48:51]
	v_mfma_f32_16x16x32_bf16 v[36:39], v[206:209], v[226:229], v[36:39]
	v_mfma_f32_16x16x32_bf16 v[32:35], v[214:217], v[226:229], v[32:35]
	v_mfma_f32_16x16x32_bf16 v[20:23], v[206:209], v[234:237], v[20:23]
	v_mfma_f32_16x16x32_bf16 v[16:19], v[214:217], v[234:237], v[16:19]
	v_mfma_f32_16x16x32_bf16 v[4:7], v[206:209], v[242:245], v[4:7]
	v_mfma_f32_16x16x32_bf16 v[0:3], v[214:217], v[242:245], v[0:3]
	v_mfma_f32_16x16x32_bf16 v[52:55], v[210:213], v[222:225], v[52:55]
	v_mfma_f32_16x16x32_bf16 v[48:51], v[218:221], v[222:225], v[48:51]
	v_mfma_f32_16x16x32_bf16 v[36:39], v[210:213], v[230:233], v[36:39]
	v_mfma_f32_16x16x32_bf16 v[32:35], v[218:221], v[230:233], v[32:35]
	v_mfma_f32_16x16x32_bf16 v[20:23], v[210:213], v[238:241], v[20:23]
	v_mfma_f32_16x16x32_bf16 v[16:19], v[218:221], v[238:241], v[16:19]
	v_mfma_f32_16x16x32_bf16 v[4:7], v[210:213], v[246:249], v[4:7]
	v_mfma_f32_16x16x32_bf16 v[0:3], v[218:221], v[246:249], v[0:3]
	s_barrier
	s_setprio 0
	s_add_i32 s59, 0, 0x18000
	v_add_u32_e32 v144, s59, v197
	s_add_i32 s60, 0, 0x1c000
	ds_read_b128 v[132:135], v144
	ds_read_b128 v[136:139], v144 offset:1024
	ds_read_b128 v[140:143], v144 offset:2048
	ds_read_b128 v[180:183], v144 offset:3072
	v_add_u32_e32 v144, s60, v197
	ds_read_b128 v[202:205], v144
	ds_read_b128 v[206:209], v144 offset:1024
	ds_read_b128 v[210:213], v144 offset:2048
	ds_read_b128 v[214:217], v144 offset:3072
	s_add_u32 s6, s6, 0x40000
	s_addc_u32 s7, s7, 0
	s_mov_b32 m0, s27
	v_lshl_add_u64 v[190:191], s[6:7], 0, v[156:157]
	ds_read_b128 v[218:221], v199 offset:32768
	ds_read_b128 v[222:225], v199 offset:33792
	ds_read_b128 v[226:229], v199 offset:34816
	ds_read_b128 v[230:233], v199 offset:35840
	ds_read_b128 v[234:237], v199 offset:36864
	ds_read_b128 v[238:241], v199 offset:37888
	ds_read_b128 v[242:245], v199 offset:38912
	ds_read_b128 v[246:249], v199 offset:39936
	global_load_lds_dwordx4 v[190:191], off
	v_lshl_add_u64 v[190:191], s[6:7], 0, v[152:153]
	s_mov_b32 m0, s28
	s_nop 0
	global_load_lds_dwordx4 v[190:191], off
	s_waitcnt vmcnt(8)
	s_waitcnt lgkmcnt(0)
	.p2alignl 3, 3212836864
	s_setprio 1
	s_barrier
	v_mfma_f32_16x16x32_bf16 v[124:127], v[132:135], v[218:221], v[124:127]
	v_mfma_f32_16x16x32_bf16 v[120:123], v[140:143], v[218:221], v[120:123]
	v_mfma_f32_16x16x32_bf16 v[108:111], v[132:135], v[226:229], v[108:111]
	v_mfma_f32_16x16x32_bf16 v[104:107], v[140:143], v[226:229], v[104:107]
	v_mfma_f32_16x16x32_bf16 v[92:95], v[132:135], v[234:237], v[92:95]
	v_mfma_f32_16x16x32_bf16 v[88:91], v[140:143], v[234:237], v[88:91]
	v_mfma_f32_16x16x32_bf16 v[76:79], v[132:135], v[242:245], v[76:79]
	v_mfma_f32_16x16x32_bf16 v[72:75], v[140:143], v[242:245], v[72:75]
	v_mfma_f32_16x16x32_bf16 v[124:127], v[136:139], v[222:225], v[124:127]
	v_mfma_f32_16x16x32_bf16 v[120:123], v[180:183], v[222:225], v[120:123]
	v_mfma_f32_16x16x32_bf16 v[108:111], v[136:139], v[230:233], v[108:111]
	v_mfma_f32_16x16x32_bf16 v[104:107], v[180:183], v[230:233], v[104:107]
	v_mfma_f32_16x16x32_bf16 v[92:95], v[136:139], v[238:241], v[92:95]
	v_mfma_f32_16x16x32_bf16 v[88:91], v[180:183], v[238:241], v[88:91]
	v_mfma_f32_16x16x32_bf16 v[76:79], v[136:139], v[246:249], v[76:79]
	v_mfma_f32_16x16x32_bf16 v[72:75], v[180:183], v[246:249], v[72:75]
	s_setprio 0
	s_setprio 1
	v_mfma_f32_16x16x32_bf16 v[116:119], v[202:205], v[218:221], v[116:119]
	v_mfma_f32_16x16x32_bf16 v[112:115], v[210:213], v[218:221], v[112:115]
	v_mfma_f32_16x16x32_bf16 v[100:103], v[202:205], v[226:229], v[100:103]
	v_mfma_f32_16x16x32_bf16 v[96:99], v[210:213], v[226:229], v[96:99]
	v_mfma_f32_16x16x32_bf16 v[84:87], v[202:205], v[234:237], v[84:87]
	v_mfma_f32_16x16x32_bf16 v[80:83], v[210:213], v[234:237], v[80:83]
	v_mfma_f32_16x16x32_bf16 v[68:71], v[202:205], v[242:245], v[68:71]
	v_mfma_f32_16x16x32_bf16 v[64:67], v[210:213], v[242:245], v[64:67]
	v_mfma_f32_16x16x32_bf16 v[116:119], v[206:209], v[222:225], v[116:119]
	v_mfma_f32_16x16x32_bf16 v[112:115], v[214:217], v[222:225], v[112:115]
	v_mfma_f32_16x16x32_bf16 v[100:103], v[206:209], v[230:233], v[100:103]
	v_mfma_f32_16x16x32_bf16 v[96:99], v[214:217], v[230:233], v[96:99]
	v_mfma_f32_16x16x32_bf16 v[84:87], v[206:209], v[238:241], v[84:87]
	v_mfma_f32_16x16x32_bf16 v[80:83], v[214:217], v[238:241], v[80:83]
	v_mfma_f32_16x16x32_bf16 v[68:71], v[206:209], v[246:249], v[68:71]
	v_mfma_f32_16x16x32_bf16 v[64:67], v[214:217], v[246:249], v[64:67]
	s_barrier
; #define PG8_STAGE(bufoff, gbase, voff) do { _Pragma("unroll") for (int _i = 0; _i < 2; ++_i) \
;         __builtin_amdgcn_global_load_lds((const unsigned*)((const char*)(gbase) + (voff)[_i]), (PG8_LAS unsigned*)(lds + (bufoff) + ldsw + _i * 8192), 16, 0, 0); } while (0)
; #define PG8_LDA(dst, b, h) do { _Pragma("unroll") for (int m = 0; m < 4; ++m) _Pragma("unroll") for (int k = 0; k < 2; ++k) dst[m][k] = *(const PG8_LAS bf16x8*)(lds + PG8_SA(b, h) + aoff + m * 2048 + k * 1024); } while (0)
; #define PG8_MMA(ai, bj, At, Bt) do { __builtin_amdgcn_s_setprio(1); _Pragma("unroll") for (int m = 0; m < 4; ++m) _Pragma("unroll") for (int n = 0; n < 2; ++n) _Pragma("unroll") for (int k = 0; k < 2; ++k) \
;         acc[ai][bj][m][n] = __builtin_amdgcn_mfma_f32_16x16x32_bf16(Bt[n][k], At[m][k], acc[ai][bj][m][n], 0, 0, 0); __builtin_amdgcn_s_setprio(0); } while (0)
; #define PG8_WAIT_V(n) asm volatile("s_waitcnt vmcnt(" #n ")" ::: "memory")
; #define PG8_WAIT_L(n) asm volatile("s_waitcnt lgkmcnt(" #n ")" ::: "memory")
; #define PG8_BAR __builtin_amdgcn_s_barrier()
; #define PG8_SCHED __builtin_amdgcn_sched_barrier(0)
; template <class Epi, class Sched, bool ALIGN_EPI = false, bool SP2 = false>
; __device__ __forceinline__ void gemm_phase(PG8_LAS unsigned char* lds, const Gemm g, const Sched& S, const Epi& E) {
;     ...
;             PG8_LDA(At, 1, 1); PG8_STAGE(PG8_SB(1, 0), b3, voffB); PG8_STAGE(PG8_SB(1, 1), b3 + hstep, voffB); PG8_STAGE(PG8_SA(1, 0), a3, voffA);
;             PG8_WAIT_V(8); PG8_WAIT_L(0); PG8_BAR; PG8_MMA(1, 0, At, B0); PG8_MMA(1, 1, At, B1); PG8_BAR; PG8_SCHED;
	s_setprio 0
	s_add_i32 s6, s59, s24
	v_lshl_add_u64 v[172:173], v[172:173], 0, s[94:95]
	s_mov_b32 m0, s6
	ds_read_b128 v[218:221], v199 offset:49152
	ds_read_b128 v[222:225], v199 offset:50176
	ds_read_b128 v[226:229], v199 offset:51200
	ds_read_b128 v[230:233], v199 offset:52224
	ds_read_b128 v[234:237], v199 offset:53248
	ds_read_b128 v[238:241], v199 offset:54272
	ds_read_b128 v[242:245], v199 offset:55296
	ds_read_b128 v[246:249], v199 offset:56320
	global_load_lds_dwordx4 v[172:173], off
	s_add_i32 m0, s6, 0x2000
	s_add_u32 s0, s0, 0x40080
	v_lshl_add_u64 v[172:173], v[184:185], 0, s[94:95]
	s_addc_u32 s1, s1, 0
	s_add_i32 s6, s60, s24
	global_load_lds_dwordx4 v[172:173], off
	v_lshl_add_u64 v[172:173], s[0:1], 0, v[154:155]
	s_mov_b32 m0, s6
	s_nop 0
	global_load_lds_dwordx4 v[172:173], off
	v_lshl_add_u64 v[172:173], s[0:1], 0, v[150:151]
	s_add_i32 m0, s6, 0x2000
	s_nop 0
	global_load_lds_dwordx4 v[172:173], off
	v_lshl_add_u64 v[172:173], v[186:187], 0, s[94:95]
	s_mov_b32 m0, s29
	s_nop 0
	global_load_lds_dwordx4 v[172:173], off
	v_lshl_add_u64 v[172:173], v[188:189], 0, s[94:95]
	s_mov_b32 m0, s30
	s_nop 0
	global_load_lds_dwordx4 v[172:173], off
	s_waitcnt vmcnt(8)
	s_waitcnt lgkmcnt(0)
	.p2alignl 3, 3212836864
	s_setprio 1
	s_barrier
	v_mfma_f32_16x16x32_bf16 v[60:63], v[132:135], v[218:221], v[60:63]
	v_mfma_f32_16x16x32_bf16 v[56:59], v[140:143], v[218:221], v[56:59]
	v_mfma_f32_16x16x32_bf16 v[44:47], v[132:135], v[226:229], v[44:47]
	v_mfma_f32_16x16x32_bf16 v[40:43], v[140:143], v[226:229], v[40:43]
	v_mfma_f32_16x16x32_bf16 v[28:31], v[132:135], v[234:237], v[28:31]
	v_mfma_f32_16x16x32_bf16 v[24:27], v[140:143], v[234:237], v[24:27]
	v_mfma_f32_16x16x32_bf16 v[12:15], v[132:135], v[242:245], v[12:15]
	v_mfma_f32_16x16x32_bf16 v[8:11], v[140:143], v[242:245], v[8:11]
	v_mfma_f32_16x16x32_bf16 v[60:63], v[136:139], v[222:225], v[60:63]
	v_mfma_f32_16x16x32_bf16 v[56:59], v[180:183], v[222:225], v[56:59]
	v_mfma_f32_16x16x32_bf16 v[44:47], v[136:139], v[230:233], v[44:47]
	v_mfma_f32_16x16x32_bf16 v[40:43], v[180:183], v[230:233], v[40:43]
	v_mfma_f32_16x16x32_bf16 v[28:31], v[136:139], v[238:241], v[28:31]
	v_mfma_f32_16x16x32_bf16 v[24:27], v[180:183], v[238:241], v[24:27]
	v_mfma_f32_16x16x32_bf16 v[12:15], v[136:139], v[246:249], v[12:15]
	v_mfma_f32_16x16x32_bf16 v[8:11], v[180:183], v[246:249], v[8:11]
	s_setprio 0
	s_setprio 1
	v_mfma_f32_16x16x32_bf16 v[52:55], v[202:205], v[218:221], v[52:55]
	v_mfma_f32_16x16x32_bf16 v[48:51], v[210:213], v[218:221], v[48:51]
	v_mfma_f32_16x16x32_bf16 v[36:39], v[202:205], v[226:229], v[36:39]
	v_mfma_f32_16x16x32_bf16 v[32:35], v[210:213], v[226:229], v[32:35]
	v_mfma_f32_16x16x32_bf16 v[20:23], v[202:205], v[234:237], v[20:23]
	v_mfma_f32_16x16x32_bf16 v[16:19], v[210:213], v[234:237], v[16:19]
	v_mfma_f32_16x16x32_bf16 v[4:7], v[202:205], v[242:245], v[4:7]
	v_mfma_f32_16x16x32_bf16 v[0:3], v[210:213], v[242:245], v[0:3]
	v_mfma_f32_16x16x32_bf16 v[52:55], v[206:209], v[222:225], v[52:55]
	v_mfma_f32_16x16x32_bf16 v[48:51], v[214:217], v[222:225], v[48:51]
	v_mfma_f32_16x16x32_bf16 v[36:39], v[206:209], v[230:233], v[36:39]
	v_mfma_f32_16x16x32_bf16 v[32:35], v[214:217], v[230:233], v[32:35]
	v_mfma_f32_16x16x32_bf16 v[20:23], v[206:209], v[238:241], v[20:23]
	v_mfma_f32_16x16x32_bf16 v[16:19], v[214:217], v[238:241], v[16:19]
	v_mfma_f32_16x16x32_bf16 v[4:7], v[206:209], v[246:249], v[4:7]
	v_mfma_f32_16x16x32_bf16 v[0:3], v[214:217], v[246:249], v[0:3]
	s_barrier
	s_setprio 0
	s_add_i32 s58, s58, 2
	s_add_u32 s4, s4, 0x100
	s_addc_u32 s5, s5, 0
	s_add_u32 s56, s56, 0x100
	s_addc_u32 s57, s57, 0
	s_cmp_gt_u32 s58, 13
	s_cbranch_scc1 .LBB0_247

; #define PG8_STAGE(bufoff, gbase, voff) do { _Pragma("unroll") for (int _i = 0; _i < 2; ++_i) \
;         __builtin_amdgcn_global_load_lds((const unsigned*)((const char*)(gbase) + (voff)[_i]), (PG8_LAS unsigned*)(lds + (bufoff) + ldsw + _i * 8192), 16, 0, 0); } while (0)
; #define PG8_LDA(dst, b, h) do { _Pragma("unroll") for (int m = 0; m < 4; ++m) _Pragma("unroll") for (int k = 0; k < 2; ++k) dst[m][k] = *(const PG8_LAS bf16x8*)(lds + PG8_SA(b, h) + aoff + m * 2048 + k * 1024); } while (0)
; #define PG8_LDB(dst, b, h) do { _Pragma("unroll") for (int n = 0; n < 2; ++n) _Pragma("unroll") for (int k = 0; k < 2; ++k) dst[n][k] = *(const PG8_LAS bf16x8*)(lds + PG8_SB(b, h) + boff + n * 2048 + k * 1024); } while (0)
; #define PG8_MMA(ai, bj, At, Bt) do { __builtin_amdgcn_s_setprio(1); _Pragma("unroll") for (int m = 0; m < 4; ++m) _Pragma("unroll") for (int n = 0; n < 2; ++n) _Pragma("unroll") for (int k = 0; k < 2; ++k) \
;         acc[ai][bj][m][n] = __builtin_amdgcn_mfma_f32_16x16x32_bf16(Bt[n][k], At[m][k], acc[ai][bj][m][n], 0, 0, 0); __builtin_amdgcn_s_setprio(0); } while (0)
; #define PG8_WAIT_V(n) asm volatile("s_waitcnt vmcnt(" #n ")" ::: "memory")
; #define PG8_WAIT_L(n) asm volatile("s_waitcnt lgkmcnt(" #n ")" ::: "memory")
; #define PG8_BAR __builtin_amdgcn_s_barrier()
; template <class Epi, class Sched, bool ALIGN_EPI = false, bool SP2 = false>
; __device__ __forceinline__ void gemm_phase(PG8_LAS unsigned char* lds, const Gemm g, const Sched& S, const Epi& E) {
;     ...
;             PG8_LDB(B0, 0, 0); PG8_LDB(B1, 0, 1); PG8_SCHED; PG8_LDA(At, 0, 0); PG8_STAGE(PG8_SA(1, 1), a1 + hstep, voffA);
;             PG8_WAIT_V(8); PG8_WAIT_L(0); PG8_BAR; PG8_MMA(0, 0, At, B0); PG8_MMA(0, 1, At, B1); PG8_BAR; PG8_SCHED;
;             PG8_LDA(At, 0, 1); PG8_STAGE(PG8_SB(0, 0), b2, voffB); PG8_STAGE(PG8_SB(0, 1), b2 + hstep, voffB); PG8_STAGE(PG8_SA(0, 0), a2, voffA);
;             PG8_WAIT_V(8); PG8_WAIT_L(0); PG8_BAR; PG8_MMA(1, 0, At, B0); PG8_MMA(1, 1, At, B1); PG8_BAR; PG8_SCHED;
;     __device__ __forceinline__ void finish(f32x4 (&acc)[2][2][4][2], const Pre&) const {
; #pragma unroll
;         for (int a = 0; a < 2; ++a)
; #pragma unroll
;             for (int b = 0; b < 2; ++b)
; #pragma unroll
;                 for (int m = 0; m < 4; ++m)
; #pragma unroll
;                     for (int n = 0; n < 2; ++n) acc[a][b][m][n] = (f32x4){0.f, 0.f, 0.f, 0.f};
;     }
.Lwin_peel:
	s_mov_b64 s[0:1], 0
	s_add_u32 s6, s4, 0xfffc0080
	s_addc_u32 s7, s5, -1
	s_and_b64 s[0:1], s[0:1], exec
	s_cselect_b32 s7, s38, s7
	s_cselect_b32 s6, s39, s6
	s_cselect_b32 s1, s49, s57
	s_cselect_b32 s0, s55, s56
	s_cmp_eq_u32 s58, -2
	s_cselect_b32 vcc_lo, 1, 0
	s_cmp_gt_u32 s34, 1
	s_cselect_b32 vcc_lo, vcc_lo, 0
	s_add_i32 s59, 0, 0x10000
	s_add_i32 s62, 0, 0x14000
	v_lshl_add_u64 v[172:173], s[4:5], 0, v[166:167]
	s_add_i32 m0, s25, 0xc000
	global_load_lds_dwordx4 v[172:173], off
	v_lshl_add_u64 v[172:173], s[4:5], 0, v[168:169]
	s_add_i32 m0, s25, 0xe000
	s_nop 0
	global_load_lds_dwordx4 v[172:173], off
	s_waitcnt vmcnt(24)
	s_cmp_lg_u32 vcc_lo, 0
	s_cbranch_scc1 .Lwin_relaxed0_p
	s_waitcnt vmcnt(8)
.Lwin_relaxed0_p:
	s_waitcnt lgkmcnt(0)
	.p2alignl 3, 3212836864
	s_setprio 1
	s_barrier
	v_mfma_f32_16x16x32_bf16 v[124:127], v[132:135], v[222:225], 0
	v_mfma_f32_16x16x32_bf16 v[120:123], v[140:143], v[222:225], 0
	v_mfma_f32_16x16x32_bf16 v[108:111], v[132:135], v[230:233], 0
	v_mfma_f32_16x16x32_bf16 v[104:107], v[140:143], v[230:233], 0
	v_mfma_f32_16x16x32_bf16 v[92:95], v[132:135], v[238:241], 0
	v_mfma_f32_16x16x32_bf16 v[88:91], v[140:143], v[238:241], 0
	v_mfma_f32_16x16x32_bf16 v[76:79], v[132:135], v[246:249], 0
	v_mfma_f32_16x16x32_bf16 v[72:75], v[140:143], v[246:249], 0
	v_mfma_f32_16x16x32_bf16 v[124:127], v[136:139], v[226:229], v[124:127]
	v_mfma_f32_16x16x32_bf16 v[120:123], v[202:205], v[226:229], v[120:123]
	v_mfma_f32_16x16x32_bf16 v[108:111], v[136:139], v[234:237], v[108:111]
	v_mfma_f32_16x16x32_bf16 v[104:107], v[202:205], v[234:237], v[104:107]
	v_mfma_f32_16x16x32_bf16 v[92:95], v[136:139], v[242:245], v[92:95]
	v_mfma_f32_16x16x32_bf16 v[88:91], v[202:205], v[242:245], v[88:91]
	v_mfma_f32_16x16x32_bf16 v[76:79], v[136:139], v[180:183], v[76:79]
	v_mfma_f32_16x16x32_bf16 v[72:75], v[202:205], v[180:183], v[72:75]
	s_setprio 0
	s_setprio 1
	v_mfma_f32_16x16x32_bf16 v[116:119], v[206:209], v[222:225], 0
	v_mfma_f32_16x16x32_bf16 v[112:115], v[214:217], v[222:225], 0
	v_mfma_f32_16x16x32_bf16 v[100:103], v[206:209], v[230:233], 0
	v_mfma_f32_16x16x32_bf16 v[96:99], v[214:217], v[230:233], 0
	v_mfma_f32_16x16x32_bf16 v[84:87], v[206:209], v[238:241], 0
	v_mfma_f32_16x16x32_bf16 v[80:83], v[214:217], v[238:241], 0
	v_mfma_f32_16x16x32_bf16 v[68:71], v[206:209], v[246:249], 0
	v_mfma_f32_16x16x32_bf16 v[64:67], v[214:217], v[246:249], 0
	v_mfma_f32_16x16x32_bf16 v[116:119], v[210:213], v[226:229], v[116:119]
	v_mfma_f32_16x16x32_bf16 v[112:115], v[218:221], v[226:229], v[112:115]
	v_mfma_f32_16x16x32_bf16 v[100:103], v[210:213], v[234:237], v[100:103]
	v_mfma_f32_16x16x32_bf16 v[96:99], v[218:221], v[234:237], v[96:99]
	v_mfma_f32_16x16x32_bf16 v[84:87], v[210:213], v[242:245], v[84:87]
	v_mfma_f32_16x16x32_bf16 v[80:83], v[218:221], v[242:245], v[80:83]
	v_mfma_f32_16x16x32_bf16 v[68:71], v[210:213], v[180:183], v[68:71]
	v_mfma_f32_16x16x32_bf16 v[64:67], v[218:221], v[180:183], v[64:67]
	s_barrier
	s_setprio 0
	s_add_i32 s59, s59, s24
	v_lshl_add_u64 v[172:173], s[0:1], 0, v[154:155]
	s_mov_b32 m0, s59
	ds_read_b128 v[180:183], v199 offset:16384
	ds_read_b128 v[222:225], v199 offset:17408
	ds_read_b128 v[226:229], v199 offset:18432
	ds_read_b128 v[230:233], v199 offset:19456
	ds_read_b128 v[234:237], v199 offset:20480
	ds_read_b128 v[238:241], v199 offset:21504
	ds_read_b128 v[242:245], v199 offset:22528
	ds_read_b128 v[246:249], v199 offset:23552
	global_load_lds_dwordx4 v[172:173], off
	s_add_i32 m0, s59, 0x2000
	s_add_u32 s60, s0, 0x40000
	v_lshl_add_u64 v[184:185], s[0:1], 0, v[150:151]
	s_addc_u32 s61, s1, 0
	s_add_i32 s59, s62, s24
	global_load_lds_dwordx4 v[184:185], off
	v_lshl_add_u64 v[186:187], s[60:61], 0, v[154:155]
	s_mov_b32 m0, s59
	v_lshl_add_u64 v[188:189], s[6:7], 0, v[152:153]
	global_load_lds_dwordx4 v[186:187], off
	v_lshl_add_u64 v[186:187], s[60:61], 0, v[150:151]
	s_add_i32 m0, s59, 0x2000
	s_nop 0
	global_load_lds_dwordx4 v[186:187], off
	v_lshl_add_u64 v[186:187], s[6:7], 0, v[156:157]
	s_mov_b32 m0, s25
	s_nop 0
	global_load_lds_dwordx4 v[186:187], off
	s_mov_b32 m0, s26
	s_nop 0
	global_load_lds_dwordx4 v[188:189], off
	s_waitcnt vmcnt(24)
	s_cmp_lg_u32 vcc_lo, 0
	s_cbranch_scc1 .Lwin_relaxed1_p
	s_waitcnt vmcnt(8)
; #define PG8_STAGE(bufoff, gbase, voff) do { _Pragma("unroll") for (int _i = 0; _i < 2; ++_i) \
;         __builtin_amdgcn_global_load_lds((const unsigned*)((const char*)(gbase) + (voff)[_i]), (PG8_LAS unsigned*)(lds + (bufoff) + ldsw + _i * 8192), 16, 0, 0); } while (0)
; #define PG8_LDA(dst, b, h) do { _Pragma("unroll") for (int m = 0; m < 4; ++m) _Pragma("unroll") for (int k = 0; k < 2; ++k) dst[m][k] = *(const PG8_LAS bf16x8*)(lds + PG8_SA(b, h) + aoff + m * 2048 + k * 1024); } while (0)
; #define PG8_LDB(dst, b, h) do { _Pragma("unroll") for (int n = 0; n < 2; ++n) _Pragma("unroll") for (int k = 0; k < 2; ++k) dst[n][k] = *(const PG8_LAS bf16x8*)(lds + PG8_SB(b, h) + boff + n * 2048 + k * 1024); } while (0)
; #define PG8_MMA(ai, bj, At, Bt) do { __builtin_amdgcn_s_setprio(1); _Pragma("unroll") for (int m = 0; m < 4; ++m) _Pragma("unroll") for (int n = 0; n < 2; ++n) _Pragma("unroll") for (int k = 0; k < 2; ++k) \
;         acc[ai][bj][m][n] = __builtin_amdgcn_mfma_f32_16x16x32_bf16(Bt[n][k], At[m][k], acc[ai][bj][m][n], 0, 0, 0); __builtin_amdgcn_s_setprio(0); } while (0)
; #define PG8_WAIT_V(n) asm volatile("s_waitcnt vmcnt(" #n ")" ::: "memory")
; #define PG8_WAIT_L(n) asm volatile("s_waitcnt lgkmcnt(" #n ")" ::: "memory")
; #define PG8_BAR __builtin_amdgcn_s_barrier()
; #define PG8_SCHED __builtin_amdgcn_sched_barrier(0)
; template <class Epi, class Sched, bool ALIGN_EPI = false, bool SP2 = false>
; __device__ __forceinline__ void gemm_phase(PG8_LAS unsigned char* lds, const Gemm g, const Sched& S, const Epi& E) {
;     ...
;             PG8_WAIT_V(8); PG8_WAIT_L(0); PG8_BAR; PG8_MMA(1, 0, At, B0); PG8_MMA(1, 1, At, B1); PG8_BAR; PG8_SCHED;
;             PG8_LDB(B0, 1, 0); PG8_LDB(B1, 1, 1); PG8_SCHED; PG8_LDA(At, 1, 0); PG8_STAGE(PG8_SA(0, 1), a2 + hstep, voffA);
;             PG8_WAIT_V(8); PG8_WAIT_L(0); PG8_BAR; PG8_MMA(0, 0, At, B0); PG8_MMA(0, 1, At, B1); PG8_BAR; PG8_SCHED;
;             PG8_LDA(At, 1, 1); PG8_STAGE(PG8_SB(1, 0), b3, voffB); PG8_STAGE(PG8_SB(1, 1), b3 + hstep, voffB); PG8_STAGE(PG8_SA(1, 0), a3, voffA);
.Lwin_relaxed1_p:
	s_waitcnt lgkmcnt(0)
	.p2alignl 3, 3212836864
	s_setprio 1
	s_barrier
	v_mfma_f32_16x16x32_bf16 v[60:63], v[132:135], v[180:183], 0
	v_mfma_f32_16x16x32_bf16 v[56:59], v[140:143], v[180:183], 0
	v_mfma_f32_16x16x32_bf16 v[44:47], v[132:135], v[226:229], 0
	v_mfma_f32_16x16x32_bf16 v[40:43], v[140:143], v[226:229], 0
	v_mfma_f32_16x16x32_bf16 v[28:31], v[132:135], v[234:237], 0
	v_mfma_f32_16x16x32_bf16 v[24:27], v[140:143], v[234:237], 0
	v_mfma_f32_16x16x32_bf16 v[12:15], v[132:135], v[242:245], 0
	v_mfma_f32_16x16x32_bf16 v[8:11], v[140:143], v[242:245], 0
	v_mfma_f32_16x16x32_bf16 v[60:63], v[136:139], v[222:225], v[60:63]
	v_mfma_f32_16x16x32_bf16 v[56:59], v[202:205], v[222:225], v[56:59]
	v_mfma_f32_16x16x32_bf16 v[44:47], v[136:139], v[230:233], v[44:47]
	v_mfma_f32_16x16x32_bf16 v[40:43], v[202:205], v[230:233], v[40:43]
	v_mfma_f32_16x16x32_bf16 v[28:31], v[136:139], v[238:241], v[28:31]
	v_mfma_f32_16x16x32_bf16 v[24:27], v[202:205], v[238:241], v[24:27]
	v_mfma_f32_16x16x32_bf16 v[12:15], v[136:139], v[246:249], v[12:15]
	v_mfma_f32_16x16x32_bf16 v[8:11], v[202:205], v[246:249], v[8:11]
	s_setprio 0
	s_setprio 1
	v_mfma_f32_16x16x32_bf16 v[52:55], v[206:209], v[180:183], 0
	v_mfma_f32_16x16x32_bf16 v[48:51], v[214:217], v[180:183], 0
	v_mfma_f32_16x16x32_bf16 v[36:39], v[206:209], v[226:229], 0
	v_mfma_f32_16x16x32_bf16 v[32:35], v[214:217], v[226:229], 0
	v_mfma_f32_16x16x32_bf16 v[20:23], v[206:209], v[234:237], 0
	v_mfma_f32_16x16x32_bf16 v[16:19], v[214:217], v[234:237], 0
	v_mfma_f32_16x16x32_bf16 v[4:7], v[206:209], v[242:245], 0
	v_mfma_f32_16x16x32_bf16 v[0:3], v[214:217], v[242:245], 0
	v_mfma_f32_16x16x32_bf16 v[52:55], v[210:213], v[222:225], v[52:55]
	v_mfma_f32_16x16x32_bf16 v[48:51], v[218:221], v[222:225], v[48:51]
	v_mfma_f32_16x16x32_bf16 v[36:39], v[210:213], v[230:233], v[36:39]
	v_mfma_f32_16x16x32_bf16 v[32:35], v[218:221], v[230:233], v[32:35]
	v_mfma_f32_16x16x32_bf16 v[20:23], v[210:213], v[238:241], v[20:23]
	v_mfma_f32_16x16x32_bf16 v[16:19], v[218:221], v[238:241], v[16:19]
	v_mfma_f32_16x16x32_bf16 v[4:7], v[210:213], v[246:249], v[4:7]
	v_mfma_f32_16x16x32_bf16 v[0:3], v[218:221], v[246:249], v[0:3]
	s_barrier
	s_setprio 0
	s_add_i32 s59, 0, 0x18000
	v_add_u32_e32 v144, s59, v197
	s_add_i32 s60, 0, 0x1c000
	ds_read_b128 v[132:135], v144
	ds_read_b128 v[136:139], v144 offset:1024
	ds_read_b128 v[140:143], v144 offset:2048
	ds_read_b128 v[180:183], v144 offset:3072
	v_add_u32_e32 v144, s60, v197
	ds_read_b128 v[202:205], v144
	ds_read_b128 v[206:209], v144 offset:1024
	ds_read_b128 v[210:213], v144 offset:2048
	ds_read_b128 v[214:217], v144 offset:3072
	s_add_u32 s6, s6, 0x40000
	s_addc_u32 s7, s7, 0
	s_mov_b32 m0, s27
	v_lshl_add_u64 v[190:191], s[6:7], 0, v[156:157]
	ds_read_b128 v[218:221], v199 offset:32768
	ds_read_b128 v[222:225], v199 offset:33792
	ds_read_b128 v[226:229], v199 offset:34816
	ds_read_b128 v[230:233], v199 offset:35840
	ds_read_b128 v[234:237], v199 offset:36864
	ds_read_b128 v[238:241], v199 offset:37888
	ds_read_b128 v[242:245], v199 offset:38912
	ds_read_b128 v[246:249], v199 offset:39936
	global_load_lds_dwordx4 v[190:191], off
	v_lshl_add_u64 v[190:191], s[6:7], 0, v[152:153]
	s_mov_b32 m0, s28
	s_nop 0
	global_load_lds_dwordx4 v[190:191], off
	s_waitcnt vmcnt(8)
	s_waitcnt lgkmcnt(0)
	.p2alignl 3, 3212836864
	s_setprio 1
	s_barrier
	v_mfma_f32_16x16x32_bf16 v[124:127], v[132:135], v[218:221], v[124:127]
	v_mfma_f32_16x16x32_bf16 v[120:123], v[140:143], v[218:221], v[120:123]
	v_mfma_f32_16x16x32_bf16 v[108:111], v[132:135], v[226:229], v[108:111]
	v_mfma_f32_16x16x32_bf16 v[104:107], v[140:143], v[226:229], v[104:107]
	v_mfma_f32_16x16x32_bf16 v[92:95], v[132:135], v[234:237], v[92:95]
	v_mfma_f32_16x16x32_bf16 v[88:91], v[140:143], v[234:237], v[88:91]
	v_mfma_f32_16x16x32_bf16 v[76:79], v[132:135], v[242:245], v[76:79]
	v_mfma_f32_16x16x32_bf16 v[72:75], v[140:143], v[242:245], v[72:75]
	v_mfma_f32_16x16x32_bf16 v[124:127], v[136:139], v[222:225], v[124:127]
	v_mfma_f32_16x16x32_bf16 v[120:123], v[180:183], v[222:225], v[120:123]
	v_mfma_f32_16x16x32_bf16 v[108:111], v[136:139], v[230:233], v[108:111]
	v_mfma_f32_16x16x32_bf16 v[104:107], v[180:183], v[230:233], v[104:107]
	v_mfma_f32_16x16x32_bf16 v[92:95], v[136:139], v[238:241], v[92:95]
	v_mfma_f32_16x16x32_bf16 v[88:91], v[180:183], v[238:241], v[88:91]
	v_mfma_f32_16x16x32_bf16 v[76:79], v[136:139], v[246:249], v[76:79]
	v_mfma_f32_16x16x32_bf16 v[72:75], v[180:183], v[246:249], v[72:75]
	s_setprio 0
	s_setprio 1
	v_mfma_f32_16x16x32_bf16 v[116:119], v[202:205], v[218:221], v[116:119]
	v_mfma_f32_16x16x32_bf16 v[112:115], v[210:213], v[218:221], v[112:115]
	v_mfma_f32_16x16x32_bf16 v[100:103], v[202:205], v[226:229], v[100:103]
	v_mfma_f32_16x16x32_bf16 v[96:99], v[210:213], v[226:229], v[96:99]
	v_mfma_f32_16x16x32_bf16 v[84:87], v[202:205], v[234:237], v[84:87]
	v_mfma_f32_16x16x32_bf16 v[80:83], v[210:213], v[234:237], v[80:83]
	v_mfma_f32_16x16x32_bf16 v[68:71], v[202:205], v[242:245], v[68:71]
	v_mfma_f32_16x16x32_bf16 v[64:67], v[210:213], v[242:245], v[64:67]
	v_mfma_f32_16x16x32_bf16 v[116:119], v[206:209], v[222:225], v[116:119]
	v_mfma_f32_16x16x32_bf16 v[112:115], v[214:217], v[222:225], v[112:115]
	v_mfma_f32_16x16x32_bf16 v[100:103], v[206:209], v[230:233], v[100:103]
	v_mfma_f32_16x16x32_bf16 v[96:99], v[214:217], v[230:233], v[96:99]
	v_mfma_f32_16x16x32_bf16 v[84:87], v[206:209], v[238:241], v[84:87]
	v_mfma_f32_16x16x32_bf16 v[80:83], v[214:217], v[238:241], v[80:83]
	v_mfma_f32_16x16x32_bf16 v[68:71], v[206:209], v[246:249], v[68:71]
	v_mfma_f32_16x16x32_bf16 v[64:67], v[214:217], v[246:249], v[64:67]
	s_barrier
; #define PG8_STAGE(bufoff, gbase, voff) do { _Pragma("unroll") for (int _i = 0; _i < 2; ++_i) \
;         __builtin_amdgcn_global_load_lds((const unsigned*)((const char*)(gbase) + (voff)[_i]), (PG8_LAS unsigned*)(lds + (bufoff) + ldsw + _i * 8192), 16, 0, 0); } while (0)
; #define PG8_LDA(dst, b, h) do { _Pragma("unroll") for (int m = 0; m < 4; ++m) _Pragma("unroll") for (int k = 0; k < 2; ++k) dst[m][k] = *(const PG8_LAS bf16x8*)(lds + PG8_SA(b, h) + aoff + m * 2048 + k * 1024); } while (0)
; #define PG8_MMA(ai, bj, At, Bt) do { __builtin_amdgcn_s_setprio(1); _Pragma("unroll") for (int m = 0; m < 4; ++m) _Pragma("unroll") for (int n = 0; n < 2; ++n) _Pragma("unroll") for (int k = 0; k < 2; ++k) \
;         acc[ai][bj][m][n] = __builtin_amdgcn_mfma_f32_16x16x32_bf16(Bt[n][k], At[m][k], acc[ai][bj][m][n], 0, 0, 0); __builtin_amdgcn_s_setprio(0); } while (0)
; #define PG8_WAIT_V(n) asm volatile("s_waitcnt vmcnt(" #n ")" ::: "memory")
; #define PG8_WAIT_L(n) asm volatile("s_waitcnt lgkmcnt(" #n ")" ::: "memory")
; #define PG8_BAR __builtin_amdgcn_s_barrier()
; #define PG8_SCHED __builtin_amdgcn_sched_barrier(0)
; template <class Epi, class Sched, bool ALIGN_EPI = false, bool SP2 = false>
; __device__ __forceinline__ void gemm_phase(PG8_LAS unsigned char* lds, const Gemm g, const Sched& S, const Epi& E) {
;     ...
;             PG8_LDA(At, 1, 1); PG8_STAGE(PG8_SB(1, 0), b3, voffB); PG8_STAGE(PG8_SB(1, 1), b3 + hstep, voffB); PG8_STAGE(PG8_SA(1, 0), a3, voffA);
;             PG8_WAIT_V(8); PG8_WAIT_L(0); PG8_BAR; PG8_MMA(1, 0, At, B0); PG8_MMA(1, 1, At, B1); PG8_BAR; PG8_SCHED;
	s_setprio 0
	s_add_i32 s6, s59, s24
	v_lshl_add_u64 v[172:173], v[172:173], 0, s[94:95]
	s_mov_b32 m0, s6
	ds_read_b128 v[218:221], v199 offset:49152
	ds_read_b128 v[222:225], v199 offset:50176
	ds_read_b128 v[226:229], v199 offset:51200
	ds_read_b128 v[230:233], v199 offset:52224
	ds_read_b128 v[234:237], v199 offset:53248
	ds_read_b128 v[238:241], v199 offset:54272
	ds_read_b128 v[242:245], v199 offset:55296
	ds_read_b128 v[246:249], v199 offset:56320
	global_load_lds_dwordx4 v[172:173], off
	s_add_i32 m0, s6, 0x2000
	s_add_u32 s0, s0, 0x40080
	v_lshl_add_u64 v[172:173], v[184:185], 0, s[94:95]
	s_addc_u32 s1, s1, 0
	s_add_i32 s6, s60, s24
	global_load_lds_dwordx4 v[172:173], off
	v_lshl_add_u64 v[172:173], s[0:1], 0, v[154:155]
	s_mov_b32 m0, s6
	s_nop 0
	global_load_lds_dwordx4 v[172:173], off
	v_lshl_add_u64 v[172:173], s[0:1], 0, v[150:151]
	s_add_i32 m0, s6, 0x2000
	s_nop 0
	global_load_lds_dwordx4 v[172:173], off
	v_lshl_add_u64 v[172:173], v[186:187], 0, s[94:95]
	s_mov_b32 m0, s29
	s_nop 0
	global_load_lds_dwordx4 v[172:173], off
	v_lshl_add_u64 v[172:173], v[188:189], 0, s[94:95]
	s_mov_b32 m0, s30
	s_nop 0
	global_load_lds_dwordx4 v[172:173], off
	s_waitcnt vmcnt(8)
	s_waitcnt lgkmcnt(0)
	.p2alignl 3, 3212836864
	s_setprio 1
	s_barrier
	v_mfma_f32_16x16x32_bf16 v[60:63], v[132:135], v[218:221], v[60:63]
	v_mfma_f32_16x16x32_bf16 v[56:59], v[140:143], v[218:221], v[56:59]
	v_mfma_f32_16x16x32_bf16 v[44:47], v[132:135], v[226:229], v[44:47]
	v_mfma_f32_16x16x32_bf16 v[40:43], v[140:143], v[226:229], v[40:43]
	v_mfma_f32_16x16x32_bf16 v[28:31], v[132:135], v[234:237], v[28:31]
	v_mfma_f32_16x16x32_bf16 v[24:27], v[140:143], v[234:237], v[24:27]
	v_mfma_f32_16x16x32_bf16 v[12:15], v[132:135], v[242:245], v[12:15]
	v_mfma_f32_16x16x32_bf16 v[8:11], v[140:143], v[242:245], v[8:11]
	v_mfma_f32_16x16x32_bf16 v[60:63], v[136:139], v[222:225], v[60:63]
	v_mfma_f32_16x16x32_bf16 v[56:59], v[180:183], v[222:225], v[56:59]
	v_mfma_f32_16x16x32_bf16 v[44:47], v[136:139], v[230:233], v[44:47]
	v_mfma_f32_16x16x32_bf16 v[40:43], v[180:183], v[230:233], v[40:43]
	v_mfma_f32_16x16x32_bf16 v[28:31], v[136:139], v[238:241], v[28:31]
	v_mfma_f32_16x16x32_bf16 v[24:27], v[180:183], v[238:241], v[24:27]
	v_mfma_f32_16x16x32_bf16 v[12:15], v[136:139], v[246:249], v[12:15]
	v_mfma_f32_16x16x32_bf16 v[8:11], v[180:183], v[246:249], v[8:11]
	s_setprio 0
	s_setprio 1
	v_mfma_f32_16x16x32_bf16 v[52:55], v[202:205], v[218:221], v[52:55]
	v_mfma_f32_16x16x32_bf16 v[48:51], v[210:213], v[218:221], v[48:51]
	v_mfma_f32_16x16x32_bf16 v[36:39], v[202:205], v[226:229], v[36:39]
	v_mfma_f32_16x16x32_bf16 v[32:35], v[210:213], v[226:229], v[32:35]
	v_mfma_f32_16x16x32_bf16 v[20:23], v[202:205], v[234:237], v[20:23]
	v_mfma_f32_16x16x32_bf16 v[16:19], v[210:213], v[234:237], v[16:19]
	v_mfma_f32_16x16x32_bf16 v[4:7], v[202:205], v[242:245], v[4:7]
	v_mfma_f32_16x16x32_bf16 v[0:3], v[210:213], v[242:245], v[0:3]
	v_mfma_f32_16x16x32_bf16 v[52:55], v[206:209], v[222:225], v[52:55]
	v_mfma_f32_16x16x32_bf16 v[48:51], v[214:217], v[222:225], v[48:51]
	v_mfma_f32_16x16x32_bf16 v[36:39], v[206:209], v[230:233], v[36:39]
	v_mfma_f32_16x16x32_bf16 v[32:35], v[214:217], v[230:233], v[32:35]
	v_mfma_f32_16x16x32_bf16 v[20:23], v[206:209], v[238:241], v[20:23]
	v_mfma_f32_16x16x32_bf16 v[16:19], v[214:217], v[238:241], v[16:19]
	v_mfma_f32_16x16x32_bf16 v[4:7], v[206:209], v[246:249], v[4:7]
	v_mfma_f32_16x16x32_bf16 v[0:3], v[214:217], v[246:249], v[0:3]
	s_barrier
	s_setprio 0
	s_add_i32 s58, s58, 2
	s_add_u32 s4, s4, 0x100
	s_addc_u32 s5, s5, 0
	s_add_u32 s56, s56, 0x100
	s_addc_u32 s57, s57, 0
	s_cmp_gt_u32 s58, 13
	s_branch .LBB0_245

; #define LAS __attribute__((address_space(3)))
; __device__ __forceinline__ void rows_rstd(LAS unsigned char* sl, int rl0, int fq, float (&rs)[8]) {
;     f32x4 v[8];
; #pragma unroll
;     for (int i = 0; i < 8; ++i) v[i] = *(const LAS f32x4*)(sl + (rl0 + (i >> 2) * 128 + (i & 3) * 16) * 64 + fq * 16);
; #pragma unroll
;     for (int i = 0; i < 8; ++i) { float s = (v[i].x + v[i].y) + (v[i].z + v[i].w); s += __shfl_xor(s, 16); s += __shfl_xor(s, 32); rs[i] = rsqrtf(s * (1.0f / DM) + EPS); }
; }
;     __device__ __forceinline__ void operator()(const f32x4 (&acc)[2][2][4][2], const pg8::Unit& u, int wr, int wc, int fr, int fq) const {
;         const int row0 = u.pm * 256 + wr * 64 + fr, pn = u.pn;
;         float rs[8]; rows_rstd(sl, wr * 64 + fr, fq, rs);
;         if (pn >= 1 && pn <= 4) {
.LBB0_249:
	s_add_i32 s4, s45, -1
	s_cmp_gt_u32 s4, 3
	s_cbranch_scc1 .Lwin_act
	s_cmp_lt_u32 s45, 3
	s_cbranch_scc1 .Lrope_q
	v_and_b32_e32 v171, 64, v175
	v_xor_b32_e32 v144, 16, v175
	v_add_u32_e32 v171, 64, v171
	v_cmp_lt_i32_e32 vcc, v144, v171
	v_xor_b32_e32 v172, 32, v175
	ds_read_b128 v[180:183], v200
	ds_read_b128 v[202:205], v200 offset:1024
	ds_read_b128 v[208:211], v200 offset:2048
	ds_read_b128 v[212:215], v200 offset:3072
	ds_read_b128 v[140:143], v200 offset:8192
	ds_read_b128 v[136:139], v200 offset:9216
	ds_read_b128 v[132:135], v200 offset:10240
	ds_read_b128 v[128:131], v200 offset:11264
	v_cndmask_b32_e32 v144, v175, v144, vcc
	v_cmp_lt_i32_e32 vcc, v172, v171
	s_waitcnt lgkmcnt(0)
	v_mov_b32_e32 v173, v182
	v_lshlrev_b32_e32 v144, 2, v144
	v_cndmask_b32_e32 v171, v175, v172, vcc
	v_mov_b32_e32 v172, v181
	v_mov_b32_e32 v181, v183
	v_pk_add_f32 v[172:173], v[172:173], v[180:181]
	v_mov_b32_e32 v180, v203
	v_mov_b32_e32 v181, v204
	v_mov_b32_e32 v203, v205
	v_pk_add_f32 v[180:181], v[180:181], v[202:203]
	v_mov_b32_e32 v183, v172
	v_mov_b32_e32 v182, v180
	v_mov_b32_e32 v172, v181
	v_pk_add_f32 v[172:173], v[182:183], v[172:173]
	ds_bpermute_b32 v181, v144, v173
	ds_bpermute_b32 v180, v144, v172
	v_lshlrev_b32_e32 v186, 2, v171
	s_mov_b32 s0, 0x358637bd
	v_mov_b32_e32 v182, v213
	v_mov_b32_e32 v183, v214
	s_waitcnt lgkmcnt(0)
	v_pk_add_f32 v[172:173], v[172:173], v[180:181]
	ds_bpermute_b32 v181, v186, v173
	ds_bpermute_b32 v180, v186, v172
	v_mov_b32_e32 v213, v215
	v_pk_add_f32 v[182:183], v[182:183], v[212:213]
	s_add_i32 s4, s45, -1
	v_mov_b32_e32 v184, v182
	s_waitcnt lgkmcnt(0)
	v_pk_add_f32 v[180:181], v[172:173], v[180:181]
	v_mov_b64_e32 v[172:173], s[0:1]
	s_mov_b32 s0, 0x3a800000
	v_pk_fma_f32 v[180:181], v[180:181], s[0:1], v[172:173] op_sel_hi:[1,0,0]
	v_add_u32_e32 v201, s47, v159
	v_mul_f32_e32 v171, 0x4b800000, v181
	v_cmp_gt_f32_e64 s[38:39], s33, v181
	v_cmp_gt_f32_e32 vcc, s33, v180
	s_cmp_gt_u32 s4, 3
	v_cndmask_b32_e64 v171, v181, v171, s[38:39]
	v_rsq_f32_e32 v171, v171
	s_nop 0
	v_mul_f32_e32 v181, 0x45800000, v171
	v_cndmask_b32_e64 v171, v171, v181, s[38:39]
	v_mul_f32_e32 v181, 0x4b800000, v180
	v_cndmask_b32_e32 v180, v180, v181, vcc
	v_rsq_f32_e32 v180, v180
	s_nop 0
	v_mul_f32_e32 v181, 0x45800000, v180
	v_cndmask_b32_e32 v206, v180, v181, vcc
	v_mov_b32_e32 v180, v209
	v_mov_b32_e32 v181, v210
	v_mov_b32_e32 v209, v211
	v_pk_add_f32 v[180:181], v[180:181], v[208:209]
	s_nop 0
	v_mov_b32_e32 v185, v180
	v_mov_b32_e32 v180, v183
	v_pk_add_f32 v[180:181], v[184:185], v[180:181]
	ds_bpermute_b32 v183, v144, v181
	ds_bpermute_b32 v182, v144, v180
	s_waitcnt lgkmcnt(0)
	v_pk_add_f32 v[180:181], v[180:181], v[182:183]
	ds_bpermute_b32 v183, v186, v181
	ds_bpermute_b32 v182, v186, v180
	s_waitcnt lgkmcnt(0)
	v_pk_add_f32 v[180:181], v[180:181], v[182:183]
	s_nop 0
	v_pk_fma_f32 v[180:181], v[180:181], s[0:1], v[172:173] op_sel_hi:[1,0,0]
	s_nop 0
	v_mul_f32_e32 v182, 0x4b800000, v181
	v_cmp_gt_f32_e64 s[38:39], s33, v181
	v_cmp_gt_f32_e32 vcc, s33, v180
	s_nop 0
	v_cndmask_b32_e64 v181, v181, v182, s[38:39]
	v_rsq_f32_e32 v181, v181
	s_nop 0
	v_mul_f32_e32 v182, 0x45800000, v181
	v_cndmask_b32_e64 v205, v181, v182, s[38:39]
	v_mul_f32_e32 v181, 0x4b800000, v180
	v_cndmask_b32_e32 v180, v180, v181, vcc
	v_rsq_f32_e32 v180, v180
	s_nop 0
	v_mul_f32_e32 v181, 0x45800000, v180
	v_cndmask_b32_e32 v204, v180, v181, vcc
	v_mov_b32_e32 v180, v141
	v_mov_b32_e32 v181, v142
	v_mov_b32_e32 v141, v143
	v_mov_b32_e32 v142, v137
	v_mov_b32_e32 v143, v138
	v_mov_b32_e32 v137, v139
	v_pk_add_f32 v[140:141], v[180:181], v[140:141]
	v_pk_add_f32 v[136:137], v[142:143], v[136:137]
	v_mov_b32_e32 v139, v140
	v_mov_b32_e32 v138, v136
	v_mov_b32_e32 v140, v137
	v_pk_add_f32 v[136:137], v[138:139], v[140:141]
	ds_bpermute_b32 v139, v144, v137
	ds_bpermute_b32 v138, v144, v136
	s_waitcnt lgkmcnt(0)
	v_pk_add_f32 v[136:137], v[136:137], v[138:139]
	ds_bpermute_b32 v139, v186, v137
	ds_bpermute_b32 v138, v186, v136
	s_waitcnt lgkmcnt(0)
	v_pk_add_f32 v[136:137], v[136:137], v[138:139]
	s_nop 0
	v_pk_fma_f32 v[136:137], v[136:137], s[0:1], v[172:173] op_sel_hi:[1,0,0]
	s_nop 0
	v_mul_f32_e32 v138, 0x4b800000, v137
	v_cmp_gt_f32_e64 s[38:39], s33, v137
	v_cmp_gt_f32_e32 vcc, s33, v136
	s_nop 0
	v_cndmask_b32_e64 v137, v137, v138, s[38:39]
	v_rsq_f32_e32 v137, v137
	s_nop 0
	v_mul_f32_e32 v138, 0x45800000, v137
	v_cndmask_b32_e64 v203, v137, v138, s[38:39]
	v_mul_f32_e32 v137, 0x4b800000, v136
	v_cndmask_b32_e32 v136, v136, v137, vcc
	v_rsq_f32_e32 v136, v136
	s_nop 0
	v_mul_f32_e32 v137, 0x45800000, v136
	v_cndmask_b32_e32 v202, v136, v137, vcc
	v_mov_b32_e32 v136, v133
	v_mov_b32_e32 v137, v134
	v_mov_b32_e32 v133, v135
	v_mov_b32_e32 v134, v129
	v_mov_b32_e32 v135, v130
	v_mov_b32_e32 v129, v131
	v_pk_add_f32 v[132:133], v[136:137], v[132:133]
	v_pk_add_f32 v[128:129], v[134:135], v[128:129]
	v_mov_b32_e32 v131, v132
	v_mov_b32_e32 v130, v128
	v_mov_b32_e32 v132, v129
	v_pk_add_f32 v[128:129], v[130:131], v[132:133]
	ds_bpermute_b32 v131, v144, v129
	ds_bpermute_b32 v130, v144, v128
	s_waitcnt lgkmcnt(0)
	v_pk_add_f32 v[128:129], v[128:129], v[130:131]
	ds_bpermute_b32 v131, v186, v129
	ds_bpermute_b32 v130, v186, v128
	s_waitcnt lgkmcnt(0)
	v_pk_add_f32 v[128:129], v[128:129], v[130:131]
	s_nop 0
	v_pk_fma_f32 v[128:129], v[128:129], s[0:1], v[172:173] op_sel_hi:[1,0,0]
	s_mov_b64 s[0:1], -1
	v_mul_f32_e32 v130, 0x4b800000, v129
	v_cmp_gt_f32_e64 s[38:39], s33, v129
	v_cmp_gt_f32_e32 vcc, s33, v128
	s_nop 0
	v_cndmask_b32_e64 v129, v129, v130, s[38:39]
	v_rsq_f32_e32 v129, v129
	s_nop 0
	v_mul_f32_e32 v130, 0x45800000, v129
	v_cndmask_b32_e64 v173, v129, v130, s[38:39]
	v_mul_f32_e32 v129, 0x4b800000, v128
	v_cndmask_b32_e32 v128, v128, v129, vcc
	v_rsq_f32_e32 v128, v128
	s_nop 0
	v_mul_f32_e32 v129, 0x45800000, v128
	v_cndmask_b32_e32 v172, v128, v129, vcc
	s_branch .LBB0_266

; #define LAS __attribute__((address_space(3)))
; __device__ __forceinline__ void rows_rstd(LAS unsigned char* sl, int rl0, int fq, float (&rs)[8]) {
;     f32x4 v[8];
; #pragma unroll
;     for (int i = 0; i < 8; ++i) v[i] = *(const LAS f32x4*)(sl + (rl0 + (i >> 2) * 128 + (i & 3) * 16) * 64 + fq * 16);
; #pragma unroll
;     for (int i = 0; i < 8; ++i) { float s = (v[i].x + v[i].y) + (v[i].z + v[i].w); s += __shfl_xor(s, 16); s += __shfl_xor(s, 32); rs[i] = rsqrtf(s * (1.0f / DM) + EPS); }
; }
.Lrope_q:
	v_and_b32_e32 v171, 64, v175
	v_xor_b32_e32 v144, 16, v175
	v_add_u32_e32 v171, 64, v171
	v_cmp_lt_i32_e32 vcc, v144, v171
	v_xor_b32_e32 v172, 32, v175
	ds_read_b128 v[180:183], v200
	ds_read_b128 v[202:205], v200 offset:1024
	ds_read_b128 v[208:211], v200 offset:2048
	ds_read_b128 v[212:215], v200 offset:3072
	ds_read_b128 v[140:143], v200 offset:8192
	ds_read_b128 v[136:139], v200 offset:9216
	ds_read_b128 v[132:135], v200 offset:10240
	ds_read_b128 v[128:131], v200 offset:11264
	v_cndmask_b32_e32 v144, v175, v144, vcc
	v_cmp_lt_i32_e32 vcc, v172, v171
	s_waitcnt lgkmcnt(0)
	v_mov_b32_e32 v173, v182
	v_lshlrev_b32_e32 v144, 2, v144
	v_cndmask_b32_e32 v171, v175, v172, vcc
	v_mov_b32_e32 v172, v181
	v_mov_b32_e32 v181, v183
	v_pk_add_f32 v[172:173], v[172:173], v[180:181]
	v_mov_b32_e32 v180, v203
	v_mov_b32_e32 v181, v204
	v_mov_b32_e32 v203, v205
	v_pk_add_f32 v[180:181], v[180:181], v[202:203]
	v_mov_b32_e32 v183, v172
	v_mov_b32_e32 v182, v180
	v_mov_b32_e32 v172, v181
	v_pk_add_f32 v[172:173], v[182:183], v[172:173]
	ds_bpermute_b32 v181, v144, v173
	ds_bpermute_b32 v180, v144, v172
	v_lshlrev_b32_e32 v186, 2, v171
	s_mov_b32 s0, 0x358637bd
	v_mov_b32_e32 v182, v213
	v_mov_b32_e32 v183, v214
	s_waitcnt lgkmcnt(0)
	v_pk_add_f32 v[172:173], v[172:173], v[180:181]
	ds_bpermute_b32 v181, v186, v173
	ds_bpermute_b32 v180, v186, v172
	v_mov_b32_e32 v213, v215
	v_pk_add_f32 v[182:183], v[182:183], v[212:213]
	s_add_i32 s4, s45, -1
	v_mov_b32_e32 v184, v182
	s_waitcnt lgkmcnt(0)
	v_pk_add_f32 v[180:181], v[172:173], v[180:181]
	v_mov_b64_e32 v[172:173], s[0:1]
	s_mov_b32 s0, 0x3a800000
	v_pk_fma_f32 v[180:181], v[180:181], s[0:1], v[172:173] op_sel_hi:[1,0,0]
	v_add_u32_e32 v201, s47, v159
	v_mul_f32_e32 v171, 0x4b800000, v181
	v_cmp_gt_f32_e64 s[38:39], s33, v181
	v_cmp_gt_f32_e32 vcc, s33, v180
	s_cmp_gt_u32 s4, 3
	v_cndmask_b32_e64 v171, v181, v171, s[38:39]
	v_rsq_f32_e32 v171, v171
	s_nop 0
	v_mul_f32_e32 v181, 0x45800000, v171
	v_cndmask_b32_e64 v171, v171, v181, s[38:39]
	v_mul_f32_e32 v181, 0x4b800000, v180
	v_cndmask_b32_e32 v180, v180, v181, vcc
	v_rsq_f32_e32 v180, v180
	s_nop 0
	v_mul_f32_e32 v181, 0x45800000, v180
	v_cndmask_b32_e32 v206, v180, v181, vcc
	v_mov_b32_e32 v180, v209
	v_mov_b32_e32 v181, v210
	v_mov_b32_e32 v209, v211
	v_pk_add_f32 v[180:181], v[180:181], v[208:209]
	s_nop 0
	v_mov_b32_e32 v185, v180
	v_mov_b32_e32 v180, v183
	v_pk_add_f32 v[180:181], v[184:185], v[180:181]
	ds_bpermute_b32 v183, v144, v181
	ds_bpermute_b32 v182, v144, v180
	s_waitcnt lgkmcnt(0)
	v_pk_add_f32 v[180:181], v[180:181], v[182:183]
	ds_bpermute_b32 v183, v186, v181
	ds_bpermute_b32 v182, v186, v180
	s_waitcnt lgkmcnt(0)
	v_pk_add_f32 v[180:181], v[180:181], v[182:183]
	s_nop 0
	v_pk_fma_f32 v[180:181], v[180:181], s[0:1], v[172:173] op_sel_hi:[1,0,0]
	s_nop 0
	v_mul_f32_e32 v182, 0x4b800000, v181
	v_cmp_gt_f32_e64 s[38:39], s33, v181
	v_cmp_gt_f32_e32 vcc, s33, v180
	s_nop 0
	v_cndmask_b32_e64 v181, v181, v182, s[38:39]
	v_rsq_f32_e32 v181, v181
	s_nop 0
	v_mul_f32_e32 v182, 0x45800000, v181
	v_cndmask_b32_e64 v205, v181, v182, s[38:39]
	v_mul_f32_e32 v181, 0x4b800000, v180
	v_cndmask_b32_e32 v180, v180, v181, vcc
	v_rsq_f32_e32 v180, v180
	s_nop 0
	v_mul_f32_e32 v181, 0x45800000, v180
	v_cndmask_b32_e32 v204, v180, v181, vcc
	v_mov_b32_e32 v180, v141
	v_mov_b32_e32 v181, v142
	v_mov_b32_e32 v141, v143
	v_mov_b32_e32 v142, v137
	v_mov_b32_e32 v143, v138
	v_mov_b32_e32 v137, v139
	v_pk_add_f32 v[140:141], v[180:181], v[140:141]
	v_pk_add_f32 v[136:137], v[142:143], v[136:137]
	v_mov_b32_e32 v139, v140
	v_mov_b32_e32 v138, v136
	v_mov_b32_e32 v140, v137
	v_pk_add_f32 v[136:137], v[138:139], v[140:141]
	ds_bpermute_b32 v139, v144, v137
	ds_bpermute_b32 v138, v144, v136
	s_waitcnt lgkmcnt(0)
	v_pk_add_f32 v[136:137], v[136:137], v[138:139]
	ds_bpermute_b32 v139, v186, v137
	ds_bpermute_b32 v138, v186, v136
	s_waitcnt lgkmcnt(0)
	v_pk_add_f32 v[136:137], v[136:137], v[138:139]
	s_nop 0
	v_pk_fma_f32 v[136:137], v[136:137], s[0:1], v[172:173] op_sel_hi:[1,0,0]
	s_nop 0
	v_mul_f32_e32 v138, 0x4b800000, v137
	v_cmp_gt_f32_e64 s[38:39], s33, v137
	v_cmp_gt_f32_e32 vcc, s33, v136
	s_nop 0
	v_cndmask_b32_e64 v137, v137, v138, s[38:39]
	v_rsq_f32_e32 v137, v137
	s_nop 0
	v_mul_f32_e32 v138, 0x45800000, v137
	v_cndmask_b32_e64 v203, v137, v138, s[38:39]
	v_mul_f32_e32 v137, 0x4b800000, v136
	v_cndmask_b32_e32 v136, v136, v137, vcc
	v_rsq_f32_e32 v136, v136
	s_nop 0
	v_mul_f32_e32 v137, 0x45800000, v136
	v_cndmask_b32_e32 v202, v136, v137, vcc
	v_mov_b32_e32 v136, v133
	v_mov_b32_e32 v137, v134
	v_mov_b32_e32 v133, v135
	v_mov_b32_e32 v134, v129
	v_mov_b32_e32 v135, v130
	v_mov_b32_e32 v129, v131
	v_pk_add_f32 v[132:133], v[136:137], v[132:133]
	v_pk_add_f32 v[128:129], v[134:135], v[128:129]
	v_mov_b32_e32 v131, v132
	v_mov_b32_e32 v130, v128
	v_mov_b32_e32 v132, v129
	v_pk_add_f32 v[128:129], v[130:131], v[132:133]
	ds_bpermute_b32 v131, v144, v129
	ds_bpermute_b32 v130, v144, v128
	s_waitcnt lgkmcnt(0)
	v_pk_add_f32 v[128:129], v[128:129], v[130:131]
	ds_bpermute_b32 v131, v186, v129
	ds_bpermute_b32 v130, v186, v128
	s_waitcnt lgkmcnt(0)
	v_pk_add_f32 v[128:129], v[128:129], v[130:131]
	s_nop 0
	v_pk_fma_f32 v[128:129], v[128:129], s[0:1], v[172:173] op_sel_hi:[1,0,0]
	s_mov_b64 s[0:1], -1
	v_mul_f32_e32 v130, 0x4b800000, v129
	v_cmp_gt_f32_e64 s[38:39], s33, v129
	v_cmp_gt_f32_e32 vcc, s33, v128
	s_nop 0
	v_cndmask_b32_e64 v129, v129, v130, s[38:39]
	v_rsq_f32_e32 v129, v129
	s_nop 0
	v_mul_f32_e32 v130, 0x45800000, v129
	v_cndmask_b32_e64 v173, v129, v130, s[38:39]
	v_mul_f32_e32 v129, 0x4b800000, v128
	v_cndmask_b32_e32 v128, v128, v129, vcc
	v_rsq_f32_e32 v128, v128
	s_nop 0
	v_mul_f32_e32 v129, 0x45800000, v128
	v_cndmask_b32_e32 v172, v128, v129, vcc
	s_branch .Lrope_q266
; __device__ __forceinline__ unsigned pk2(float lo, float hi) { return pg8::cvt_pk_bf16(lo, hi); }
;     __device__ __forceinline__ void operator()(const f32x4 (&acc)[2][2][4][2], const pg8::Unit& u, int wr, int wc, int fr, int fq) const {
;     ...
;         if (pn >= 1 && pn <= 4) {
;             const float qs = (pn <= 2) ? 0.08838834764831845f : 1.0f;
;             const int dd0 = 32 * (wc & 1) + 8 * fq, hh = wc >> 1;
; #pragma unroll
;             for (int ab = 0; ab < 4; ++ab) { const int ai = ab >> 1, mb = (ab & 1) * 2;
;                 f32x4 cs[4][4];
; #pragma unroll
;                 for (int m = mb; m < mb + 2; ++m) { const int pos = (row0 + ai * 128 + m * 16) & (SEQ - 1); const float* cp = rcos + pos * 64 + dd0; const float* sp = rsin + pos * 64 + dd0;
;                     cs[m][0] = *(const f32x4*)cp; cs[m][1] = *(const f32x4*)(cp + 4); cs[m][2] = *(const f32x4*)sp; cs[m][3] = *(const f32x4*)(sp + 4); }
; #pragma unroll
;                 for (int m = mb; m < mb + 2; ++m) {
;                     const int row = row0 + ai * 128 + m * 16; const float r = rs[ai * 4 + m] * qs;
;                     const f32x4 c0 = cs[m][0], c1 = cs[m][1], s0 = cs[m][2], s1 = cs[m][3];
;                     const f32x4 ta = acc[ai][0][m][0] * r, tb = acc[ai][0][m][1] * r, ua = acc[ai][1][m][0] * r, ub = acc[ai][1][m][1] * r;
;                     const f32x4 o1a = ta * c0 - ua * s0, o1b = tb * c1 - ub * s1, o2a = ta * s0 + ua * c0, o2b = tb * s1 + ub * c1;
;                     bf16* zp = Z + (size_t)row * IW + pn * 256 + hh * 128 + dd0;
;                     u32x4 w1, w2;
;                     w1.x = pk2(o1a.x, o1a.y); w1.y = pk2(o1a.z, o1a.w); w1.z = pk2(o1b.x, o1b.y); w1.w = pk2(o1b.z, o1b.w);
;                     w2.x = pk2(o2a.x, o2a.y); w2.y = pk2(o2a.z, o2a.w); w2.z = pk2(o2b.x, o2b.y); w2.w = pk2(o2b.z, o2b.w);
;                     *(u32x4*)zp = w1; *(u32x4*)(zp + 64) = w2;
;                 }
.Lrope_q266:
	s_and_b64 vcc, exec, s[0:1]
	s_cbranch_vccz .LBB0_1021
	s_cmp_lt_u32 s45, 3
	s_cselect_b64 vcc, -1, 0
	v_mov_b32_e32 v128, 0x3db504f3
	v_cndmask_b32_e32 v207, 1.0, v128, vcc
	v_lshlrev_b32_e32 v128, 8, v201
	v_and_b32_e32 v144, 0x1fcf00, v128
	v_lshl_add_u64 v[128:129], v[162:163], 0, v[144:145]
	v_lshl_add_u64 v[130:131], v[164:165], 0, v[144:145]
	global_load_dwordx4 v[180:183], v[128:129], off offset:16
	global_load_dwordx4 v[210:213], v[128:129], off
	global_load_dwordx4 v[214:217], v[130:131], off offset:16
	global_load_dwordx4 v[218:221], v[130:131], off
	v_or_b32_e32 v128, 0x1000, v144
	v_mov_b32_e32 v129, v145
	v_lshl_add_u64 v[132:133], v[162:163], 0, v[128:129]
	v_lshl_add_u64 v[140:141], v[164:165], 0, v[128:129]
	global_load_dwordx4 v[128:131], v[132:133], off offset:16
	global_load_dwordx4 v[136:139], v[132:133], off
	s_nop 0
	global_load_dwordx4 v[132:135], v[140:141], off offset:16
	s_nop 0
	global_load_dwordx4 v[140:143], v[140:141], off
	v_mul_f32_e32 v184, v207, v171
	v_pk_mul_f32 v[118:119], v[118:119], v[184:185] op_sel_hi:[1,0]
	v_pk_mul_f32 v[116:117], v[116:117], v[184:185] op_sel_hi:[1,0]
	v_pk_mul_f32 v[112:113], v[112:113], v[184:185] op_sel_hi:[1,0]
	v_pk_mul_f32 v[126:127], v[126:127], v[184:185] op_sel_hi:[1,0]
	v_pk_mul_f32 v[124:125], v[124:125], v[184:185] op_sel_hi:[1,0]
	v_pk_mul_f32 v[122:123], v[122:123], v[184:185] op_sel_hi:[1,0]
	v_pk_mul_f32 v[120:121], v[120:121], v[184:185] op_sel_hi:[1,0]
	v_pk_mul_f32 v[114:115], v[114:115], v[184:185] op_sel_hi:[1,0]
	s_lshl_b32 s82, s45, 9
	s_mov_b32 s45, s83
	v_mov_b32_e32 v171, v145
	v_lshlrev_b32_e32 v208, 6, v201
	s_waitcnt vmcnt(0)
	v_pk_mul_f32 v[190:191], v[112:113], v[214:215]
	v_pk_mul_f32 v[184:185], v[118:119], v[220:221]
	v_pk_mul_f32 v[186:187], v[116:117], v[218:219]
	v_pk_fma_f32 v[184:185], v[126:127], v[212:213], v[184:185] neg_lo:[0,0,1] neg_hi:[0,0,1]
	v_pk_fma_f32 v[186:187], v[124:125], v[210:211], v[186:187] neg_lo:[0,0,1] neg_hi:[0,0,1]
	v_pk_fma_f32 v[190:191], v[120:121], v[180:181], v[190:191] neg_lo:[0,0,1] neg_hi:[0,0,1]
	v_pk_mul_f32 v[126:127], v[126:127], v[220:221]
	v_pk_mul_f32 v[124:125], v[124:125], v[218:219]
	v_pk_mul_f32 v[120:121], v[120:121], v[214:215]
	v_pk_mul_f32 v[188:189], v[114:115], v[216:217]
	v_pk_fma_f32 v[126:127], v[118:119], v[212:213], v[126:127]
	v_pk_fma_f32 v[118:119], v[116:117], v[210:211], v[124:125]
	v_pk_mul_f32 v[116:117], v[122:123], v[216:217]
	v_pk_fma_f32 v[120:121], v[112:113], v[180:181], v[120:121]
	v_mov_b64_e32 v[112:113], s[8:9]
	v_pk_fma_f32 v[188:189], v[122:123], v[182:183], v[188:189] neg_lo:[0,0,1] neg_hi:[0,0,1]
	v_pk_fma_f32 v[122:123], v[114:115], v[182:183], v[116:117]
	v_mad_i64_i32 v[114:115], s[0:1], v201, s84, v[112:113]
	v_lshl_add_u64 v[114:115], v[114:115], 0, s[82:83]
	v_lshl_add_u64 v[114:115], v[114:115], 0, s[44:45]
	v_lshl_add_u64 v[124:125], v[114:115], 0, v[170:171]
	v_cvt_pk_bf16_f32 v114, v186, v187
	v_cvt_pk_bf16_f32 v115, v184, v185
	v_cvt_pk_bf16_f32 v116, v190, v191
	v_cvt_pk_bf16_f32 v117, v188, v189
	v_cvt_pk_bf16_f32 v118, v118, v119
	v_cvt_pk_bf16_f32 v119, v126, v127
	v_cvt_pk_bf16_f32 v120, v120, v121
	v_cvt_pk_bf16_f32 v121, v122, v123
	global_store_dwordx4 v[124:125], v[114:117], off sc1
	global_store_dwordx4 v[124:125], v[118:121], off offset:128 sc1
	v_or_b32_e32 v122, 16, v201
	v_mul_f32_e32 v114, v207, v206
	v_pk_mul_f32 v[96:97], v[96:97], v[114:115] op_sel_hi:[1,0]
	v_pk_mul_f32 v[104:105], v[104:105], v[114:115] op_sel_hi:[1,0]
	v_pk_mul_f32 v[120:121], v[96:97], v[132:133]
	v_pk_mul_f32 v[102:103], v[102:103], v[114:115] op_sel_hi:[1,0]
	v_pk_fma_f32 v[120:121], v[104:105], v[128:129], v[120:121] neg_lo:[0,0,1] neg_hi:[0,0,1]
	v_pk_mul_f32 v[104:105], v[104:105], v[132:133]
	v_pk_mul_f32 v[100:101], v[100:101], v[114:115] op_sel_hi:[1,0]
	v_pk_mul_f32 v[98:99], v[98:99], v[114:115] op_sel_hi:[1,0]
	v_pk_fma_f32 v[104:105], v[96:97], v[128:129], v[104:105]
	v_mad_i64_i32 v[96:97], s[0:1], v122, s84, v[112:113]
	v_pk_mul_f32 v[110:111], v[110:111], v[114:115] op_sel_hi:[1,0]
	v_pk_mul_f32 v[108:109], v[108:109], v[114:115] op_sel_hi:[1,0]
	v_pk_mul_f32 v[106:107], v[106:107], v[114:115] op_sel_hi:[1,0]
	v_pk_mul_f32 v[114:115], v[102:103], v[142:143]
	v_pk_mul_f32 v[116:117], v[100:101], v[140:141]
	v_pk_mul_f32 v[118:119], v[98:99], v[134:135]
	v_lshl_add_u64 v[96:97], v[96:97], 0, s[82:83]
	v_pk_fma_f32 v[114:115], v[110:111], v[138:139], v[114:115] neg_lo:[0,0,1] neg_hi:[0,0,1]
	v_pk_fma_f32 v[116:117], v[108:109], v[136:137], v[116:117] neg_lo:[0,0,1] neg_hi:[0,0,1]
	v_pk_fma_f32 v[118:119], v[106:107], v[130:131], v[118:119] neg_lo:[0,0,1] neg_hi:[0,0,1]
	v_pk_mul_f32 v[110:111], v[110:111], v[142:143]
	v_pk_mul_f32 v[108:109], v[108:109], v[140:141]
	v_pk_mul_f32 v[106:107], v[106:107], v[134:135]
	v_lshl_add_u64 v[96:97], v[96:97], 0, s[44:45]
	v_pk_fma_f32 v[102:103], v[102:103], v[138:139], v[110:111]
	v_pk_fma_f32 v[100:101], v[100:101], v[136:137], v[108:109]
	v_pk_fma_f32 v[106:107], v[98:99], v[130:131], v[106:107]
	v_lshl_add_u64 v[108:109], v[96:97], 0, v[170:171]
	v_cvt_pk_bf16_f32 v96, v116, v117
	v_cvt_pk_bf16_f32 v97, v114, v115
	v_cvt_pk_bf16_f32 v98, v120, v121
	v_cvt_pk_bf16_f32 v99, v118, v119
	v_cvt_pk_bf16_f32 v100, v100, v101
	v_cvt_pk_bf16_f32 v101, v102, v103
	v_cvt_pk_bf16_f32 v102, v104, v105
	v_cvt_pk_bf16_f32 v103, v106, v107
	global_store_dwordx4 v[108:109], v[96:99], off sc1
	global_store_dwordx4 v[108:109], v[100:103], off offset:128 sc1
	v_mul_f32_e32 v130, v207, v205
	v_or_b32_e32 v96, 0x2000, v144
	v_mov_b32_e32 v97, v145
	v_lshl_add_u64 v[98:99], v[162:163], 0, v[96:97]
	v_lshl_add_u64 v[96:97], v[164:165], 0, v[96:97]
	global_load_dwordx4 v[114:117], v[98:99], off offset:16
	global_load_dwordx4 v[118:121], v[98:99], off
	global_load_dwordx4 v[122:125], v[96:97], off offset:16
	global_load_dwordx4 v[126:129], v[96:97], off
	v_or_b32_e32 v144, 0x3000, v144
	v_lshl_add_u64 v[100:101], v[162:163], 0, v[144:145]
	v_lshl_add_u64 v[108:109], v[164:165], 0, v[144:145]
	global_load_dwordx4 v[96:99], v[100:101], off offset:16
	global_load_dwordx4 v[104:107], v[100:101], off
	s_nop 0
	global_load_dwordx4 v[100:103], v[108:109], off offset:16
	s_nop 0
	global_load_dwordx4 v[108:111], v[108:109], off
	v_pk_mul_f32 v[80:81], v[80:81], v[130:131] op_sel_hi:[1,0]
	v_pk_mul_f32 v[88:89], v[88:89], v[130:131] op_sel_hi:[1,0]
	v_or_b32_e32 v138, 32, v201
	v_pk_mul_f32 v[86:87], v[86:87], v[130:131] op_sel_hi:[1,0]
	v_pk_mul_f32 v[84:85], v[84:85], v[130:131] op_sel_hi:[1,0]
	v_pk_mul_f32 v[82:83], v[82:83], v[130:131] op_sel_hi:[1,0]
	v_pk_mul_f32 v[94:95], v[94:95], v[130:131] op_sel_hi:[1,0]
	v_pk_mul_f32 v[92:93], v[92:93], v[130:131] op_sel_hi:[1,0]
	v_pk_mul_f32 v[90:91], v[90:91], v[130:131] op_sel_hi:[1,0]
	s_waitcnt vmcnt(5)
; __device__ __forceinline__ unsigned pk2(float lo, float hi) { return pg8::cvt_pk_bf16(lo, hi); }
;     __device__ __forceinline__ void operator()(const f32x4 (&acc)[2][2][4][2], const pg8::Unit& u, int wr, int wc, int fr, int fq) const {
;     ...
;             for (int ab = 0; ab < 4; ++ab) { const int ai = ab >> 1, mb = (ab & 1) * 2;
;                 f32x4 cs[4][4];
; #pragma unroll
;                 for (int m = mb; m < mb + 2; ++m) { const int pos = (row0 + ai * 128 + m * 16) & (SEQ - 1); const float* cp = rcos + pos * 64 + dd0; const float* sp = rsin + pos * 64 + dd0;
;                     cs[m][0] = *(const f32x4*)cp; cs[m][1] = *(const f32x4*)(cp + 4); cs[m][2] = *(const f32x4*)sp; cs[m][3] = *(const f32x4*)(sp + 4); }
; #pragma unroll
;                 for (int m = mb; m < mb + 2; ++m) {
;                     const int row = row0 + ai * 128 + m * 16; const float r = rs[ai * 4 + m] * qs;
;                     const f32x4 c0 = cs[m][0], c1 = cs[m][1], s0 = cs[m][2], s1 = cs[m][3];
;                     const f32x4 ta = acc[ai][0][m][0] * r, tb = acc[ai][0][m][1] * r, ua = acc[ai][1][m][0] * r, ub = acc[ai][1][m][1] * r;
;                     const f32x4 o1a = ta * c0 - ua * s0, o1b = tb * c1 - ub * s1, o2a = ta * s0 + ua * c0, o2b = tb * s1 + ub * c1;
;                     bf16* zp = Z + (size_t)row * IW + pn * 256 + hh * 128 + dd0;
;                     u32x4 w1, w2;
;                     w1.x = pk2(o1a.x, o1a.y); w1.y = pk2(o1a.z, o1a.w); w1.z = pk2(o1b.x, o1b.y); w1.w = pk2(o1b.z, o1b.w);
;                     w2.x = pk2(o2a.x, o2a.y); w2.y = pk2(o2a.z, o2a.w); w2.z = pk2(o2b.x, o2b.y); w2.w = pk2(o2b.z, o2b.w);
;                     *(u32x4*)zp = w1; *(u32x4*)(zp + 64) = w2;
;                 }
	v_pk_mul_f32 v[136:137], v[80:81], v[122:123]
	s_nop 0
	v_pk_fma_f32 v[136:137], v[88:89], v[114:115], v[136:137] neg_lo:[0,0,1] neg_hi:[0,0,1]
	v_pk_mul_f32 v[88:89], v[88:89], v[122:123]
	s_waitcnt vmcnt(4)
	v_pk_mul_f32 v[130:131], v[86:87], v[128:129]
	v_pk_fma_f32 v[88:89], v[80:81], v[114:115], v[88:89]
	v_mad_i64_i32 v[80:81], s[0:1], v138, s84, v[112:113]
	v_pk_mul_f32 v[132:133], v[84:85], v[126:127]
	v_pk_mul_f32 v[134:135], v[82:83], v[124:125]
	v_lshl_add_u64 v[80:81], v[80:81], 0, s[82:83]
	v_pk_fma_f32 v[130:131], v[94:95], v[120:121], v[130:131] neg_lo:[0,0,1] neg_hi:[0,0,1]
	v_pk_fma_f32 v[132:133], v[92:93], v[118:119], v[132:133] neg_lo:[0,0,1] neg_hi:[0,0,1]
	v_pk_fma_f32 v[134:135], v[90:91], v[116:117], v[134:135] neg_lo:[0,0,1] neg_hi:[0,0,1]
	v_pk_mul_f32 v[94:95], v[94:95], v[128:129]
	v_pk_mul_f32 v[92:93], v[92:93], v[126:127]
	v_pk_mul_f32 v[90:91], v[90:91], v[124:125]
	v_lshl_add_u64 v[80:81], v[80:81], 0, s[44:45]
	v_pk_fma_f32 v[86:87], v[86:87], v[120:121], v[94:95]
	v_pk_fma_f32 v[84:85], v[84:85], v[118:119], v[92:93]
	v_pk_fma_f32 v[90:91], v[82:83], v[116:117], v[90:91]
	v_lshl_add_u64 v[92:93], v[80:81], 0, v[170:171]
	v_cvt_pk_bf16_f32 v80, v132, v133
	v_cvt_pk_bf16_f32 v81, v130, v131
	v_cvt_pk_bf16_f32 v82, v136, v137
	v_cvt_pk_bf16_f32 v83, v134, v135
	v_cvt_pk_bf16_f32 v84, v84, v85
	v_cvt_pk_bf16_f32 v85, v86, v87
	v_cvt_pk_bf16_f32 v86, v88, v89
	v_cvt_pk_bf16_f32 v87, v90, v91
	global_store_dwordx4 v[92:93], v[80:83], off sc1
	global_store_dwordx4 v[92:93], v[84:87], off offset:128 sc1
	v_or_b32_e32 v88, 48, v201
	v_mul_f32_e32 v80, v207, v204
	v_pk_mul_f32 v[64:65], v[64:65], v[80:81] op_sel_hi:[1,0]
	v_pk_mul_f32 v[72:73], v[72:73], v[80:81] op_sel_hi:[1,0]
	s_waitcnt vmcnt(3)
	v_pk_mul_f32 v[86:87], v[64:65], v[100:101]
	v_pk_mul_f32 v[70:71], v[70:71], v[80:81] op_sel_hi:[1,0]
	v_pk_fma_f32 v[86:87], v[72:73], v[96:97], v[86:87] neg_lo:[0,0,1] neg_hi:[0,0,1]
	v_pk_mul_f32 v[72:73], v[72:73], v[100:101]
	v_pk_mul_f32 v[68:69], v[68:69], v[80:81] op_sel_hi:[1,0]
	v_pk_mul_f32 v[66:67], v[66:67], v[80:81] op_sel_hi:[1,0]
	v_pk_fma_f32 v[72:73], v[64:65], v[96:97], v[72:73]
	v_mad_i64_i32 v[64:65], s[0:1], v88, s84, v[112:113]
	v_pk_mul_f32 v[78:79], v[78:79], v[80:81] op_sel_hi:[1,0]
	v_pk_mul_f32 v[76:77], v[76:77], v[80:81] op_sel_hi:[1,0]
	v_pk_mul_f32 v[74:75], v[74:75], v[80:81] op_sel_hi:[1,0]
	s_waitcnt vmcnt(2)
	v_pk_mul_f32 v[80:81], v[70:71], v[110:111]
	v_pk_mul_f32 v[82:83], v[68:69], v[108:109]
	v_pk_mul_f32 v[84:85], v[66:67], v[102:103]
	v_lshl_add_u64 v[64:65], v[64:65], 0, s[82:83]
	v_pk_fma_f32 v[80:81], v[78:79], v[106:107], v[80:81] neg_lo:[0,0,1] neg_hi:[0,0,1]
	v_pk_fma_f32 v[82:83], v[76:77], v[104:105], v[82:83] neg_lo:[0,0,1] neg_hi:[0,0,1]
	v_pk_fma_f32 v[84:85], v[74:75], v[98:99], v[84:85] neg_lo:[0,0,1] neg_hi:[0,0,1]
	v_pk_mul_f32 v[78:79], v[78:79], v[110:111]
	v_pk_mul_f32 v[76:77], v[76:77], v[108:109]
	v_pk_mul_f32 v[74:75], v[74:75], v[102:103]
	v_lshl_add_u64 v[64:65], v[64:65], 0, s[44:45]
	v_pk_fma_f32 v[70:71], v[70:71], v[106:107], v[78:79]
	v_pk_fma_f32 v[68:69], v[68:69], v[104:105], v[76:77]
	v_pk_fma_f32 v[74:75], v[66:67], v[98:99], v[74:75]
	v_lshl_add_u64 v[76:77], v[64:65], 0, v[170:171]
	v_cvt_pk_bf16_f32 v64, v82, v83
	v_cvt_pk_bf16_f32 v65, v80, v81
	v_cvt_pk_bf16_f32 v66, v86, v87
	v_cvt_pk_bf16_f32 v67, v84, v85
	v_cvt_pk_bf16_f32 v68, v68, v69
	v_cvt_pk_bf16_f32 v69, v70, v71
	v_cvt_pk_bf16_f32 v70, v72, v73
	v_cvt_pk_bf16_f32 v71, v74, v75
	global_store_dwordx4 v[76:77], v[64:67], off sc1
	global_store_dwordx4 v[76:77], v[68:71], off offset:128 sc1
	v_mul_f32_e32 v96, v207, v203
	v_add_u32_e32 v64, 0x2000, v208
	v_and_b32_e32 v64, 0x7f3c0, v64
	v_lshlrev_b32_e32 v144, 2, v64
	v_lshl_add_u64 v[64:65], v[162:163], 0, v[144:145]
	v_lshl_add_u64 v[66:67], v[164:165], 0, v[144:145]
	global_load_dwordx4 v[80:83], v[64:65], off offset:16
	global_load_dwordx4 v[84:87], v[64:65], off
	global_load_dwordx4 v[88:91], v[66:67], off offset:16
	global_load_dwordx4 v[92:95], v[66:67], off
	v_add_u32_e32 v64, 0x2400, v208
	v_and_b32_e32 v64, 0x7f7c0, v64
	v_lshlrev_b32_e32 v144, 2, v64
	v_lshl_add_u64 v[68:69], v[162:163], 0, v[144:145]
	v_lshl_add_u64 v[76:77], v[164:165], 0, v[144:145]
	global_load_dwordx4 v[64:67], v[68:69], off offset:16
	global_load_dwordx4 v[72:75], v[68:69], off
	s_nop 0
	global_load_dwordx4 v[68:71], v[76:77], off offset:16
	s_nop 0
	global_load_dwordx4 v[76:79], v[76:77], off
	v_pk_mul_f32 v[48:49], v[48:49], v[96:97] op_sel_hi:[1,0]
	v_pk_mul_f32 v[56:57], v[56:57], v[96:97] op_sel_hi:[1,0]
	v_add_u32_e32 v104, 0x80, v201
	v_pk_mul_f32 v[54:55], v[54:55], v[96:97] op_sel_hi:[1,0]
	v_pk_mul_f32 v[52:53], v[52:53], v[96:97] op_sel_hi:[1,0]
	v_pk_mul_f32 v[50:51], v[50:51], v[96:97] op_sel_hi:[1,0]
	v_pk_mul_f32 v[62:63], v[62:63], v[96:97] op_sel_hi:[1,0]
	v_pk_mul_f32 v[60:61], v[60:61], v[96:97] op_sel_hi:[1,0]
	v_pk_mul_f32 v[58:59], v[58:59], v[96:97] op_sel_hi:[1,0]
	s_waitcnt vmcnt(5)
	v_pk_mul_f32 v[102:103], v[48:49], v[88:89]
	s_nop 0
	v_pk_fma_f32 v[102:103], v[56:57], v[80:81], v[102:103] neg_lo:[0,0,1] neg_hi:[0,0,1]
	v_pk_mul_f32 v[56:57], v[56:57], v[88:89]
	s_waitcnt vmcnt(4)
; __device__ __forceinline__ unsigned pk2(float lo, float hi) { return pg8::cvt_pk_bf16(lo, hi); }
;     __device__ __forceinline__ void operator()(const f32x4 (&acc)[2][2][4][2], const pg8::Unit& u, int wr, int wc, int fr, int fq) const {
;     ...
;             for (int ab = 0; ab < 4; ++ab) { const int ai = ab >> 1, mb = (ab & 1) * 2;
;                 f32x4 cs[4][4];
; #pragma unroll
;                 for (int m = mb; m < mb + 2; ++m) { const int pos = (row0 + ai * 128 + m * 16) & (SEQ - 1); const float* cp = rcos + pos * 64 + dd0; const float* sp = rsin + pos * 64 + dd0;
;                     cs[m][0] = *(const f32x4*)cp; cs[m][1] = *(const f32x4*)(cp + 4); cs[m][2] = *(const f32x4*)sp; cs[m][3] = *(const f32x4*)(sp + 4); }
; #pragma unroll
;                 for (int m = mb; m < mb + 2; ++m) {
;                     const int row = row0 + ai * 128 + m * 16; const float r = rs[ai * 4 + m] * qs;
;                     const f32x4 c0 = cs[m][0], c1 = cs[m][1], s0 = cs[m][2], s1 = cs[m][3];
;                     const f32x4 ta = acc[ai][0][m][0] * r, tb = acc[ai][0][m][1] * r, ua = acc[ai][1][m][0] * r, ub = acc[ai][1][m][1] * r;
;                     const f32x4 o1a = ta * c0 - ua * s0, o1b = tb * c1 - ub * s1, o2a = ta * s0 + ua * c0, o2b = tb * s1 + ub * c1;
;                     bf16* zp = Z + (size_t)row * IW + pn * 256 + hh * 128 + dd0;
;                     u32x4 w1, w2;
;                     w1.x = pk2(o1a.x, o1a.y); w1.y = pk2(o1a.z, o1a.w); w1.z = pk2(o1b.x, o1b.y); w1.w = pk2(o1b.z, o1b.w);
;                     w2.x = pk2(o2a.x, o2a.y); w2.y = pk2(o2a.z, o2a.w); w2.z = pk2(o2b.x, o2b.y); w2.w = pk2(o2b.z, o2b.w);
;                     *(u32x4*)zp = w1; *(u32x4*)(zp + 64) = w2;
;                 }
	v_pk_mul_f32 v[96:97], v[54:55], v[94:95]
	v_pk_fma_f32 v[56:57], v[48:49], v[80:81], v[56:57]
	v_mad_i64_i32 v[48:49], s[0:1], v104, s84, v[112:113]
	v_pk_mul_f32 v[98:99], v[52:53], v[92:93]
	v_pk_mul_f32 v[100:101], v[50:51], v[90:91]
	v_lshl_add_u64 v[48:49], v[48:49], 0, s[82:83]
	v_pk_fma_f32 v[96:97], v[62:63], v[86:87], v[96:97] neg_lo:[0,0,1] neg_hi:[0,0,1]
	v_pk_fma_f32 v[98:99], v[60:61], v[84:85], v[98:99] neg_lo:[0,0,1] neg_hi:[0,0,1]
	v_pk_fma_f32 v[100:101], v[58:59], v[82:83], v[100:101] neg_lo:[0,0,1] neg_hi:[0,0,1]
	v_pk_mul_f32 v[62:63], v[62:63], v[94:95]
	v_pk_mul_f32 v[60:61], v[60:61], v[92:93]
	v_pk_mul_f32 v[58:59], v[58:59], v[90:91]
	v_lshl_add_u64 v[48:49], v[48:49], 0, s[44:45]
	v_pk_fma_f32 v[54:55], v[54:55], v[86:87], v[62:63]
	v_pk_fma_f32 v[52:53], v[52:53], v[84:85], v[60:61]
	v_pk_fma_f32 v[58:59], v[50:51], v[82:83], v[58:59]
	v_lshl_add_u64 v[60:61], v[48:49], 0, v[170:171]
	v_cvt_pk_bf16_f32 v48, v98, v99
	v_cvt_pk_bf16_f32 v49, v96, v97
	v_cvt_pk_bf16_f32 v50, v102, v103
	v_cvt_pk_bf16_f32 v51, v100, v101
	v_cvt_pk_bf16_f32 v52, v52, v53
	v_cvt_pk_bf16_f32 v53, v54, v55
	v_cvt_pk_bf16_f32 v54, v56, v57
	v_cvt_pk_bf16_f32 v55, v58, v59
	global_store_dwordx4 v[60:61], v[48:51], off sc1
	global_store_dwordx4 v[60:61], v[52:55], off offset:128 sc1
	v_add_u32_e32 v56, 0x90, v201
	v_mul_f32_e32 v48, v207, v202
	v_pk_mul_f32 v[32:33], v[32:33], v[48:49] op_sel_hi:[1,0]
	v_pk_mul_f32 v[40:41], v[40:41], v[48:49] op_sel_hi:[1,0]
	s_waitcnt vmcnt(3)
	v_pk_mul_f32 v[54:55], v[32:33], v[68:69]
	v_pk_mul_f32 v[38:39], v[38:39], v[48:49] op_sel_hi:[1,0]
	v_pk_fma_f32 v[54:55], v[40:41], v[64:65], v[54:55] neg_lo:[0,0,1] neg_hi:[0,0,1]
	v_pk_mul_f32 v[40:41], v[40:41], v[68:69]
	v_pk_mul_f32 v[36:37], v[36:37], v[48:49] op_sel_hi:[1,0]
	v_pk_mul_f32 v[34:35], v[34:35], v[48:49] op_sel_hi:[1,0]
	v_pk_fma_f32 v[40:41], v[32:33], v[64:65], v[40:41]
	v_mad_i64_i32 v[32:33], s[0:1], v56, s84, v[112:113]
	v_pk_mul_f32 v[46:47], v[46:47], v[48:49] op_sel_hi:[1,0]
	v_pk_mul_f32 v[44:45], v[44:45], v[48:49] op_sel_hi:[1,0]
	v_pk_mul_f32 v[42:43], v[42:43], v[48:49] op_sel_hi:[1,0]
	s_waitcnt vmcnt(2)
	v_pk_mul_f32 v[48:49], v[38:39], v[78:79]
	v_pk_mul_f32 v[50:51], v[36:37], v[76:77]
	v_pk_mul_f32 v[52:53], v[34:35], v[70:71]
	v_lshl_add_u64 v[32:33], v[32:33], 0, s[82:83]
	v_pk_fma_f32 v[48:49], v[46:47], v[74:75], v[48:49] neg_lo:[0,0,1] neg_hi:[0,0,1]
	v_pk_fma_f32 v[50:51], v[44:45], v[72:73], v[50:51] neg_lo:[0,0,1] neg_hi:[0,0,1]
	v_pk_fma_f32 v[52:53], v[42:43], v[66:67], v[52:53] neg_lo:[0,0,1] neg_hi:[0,0,1]
	v_pk_mul_f32 v[46:47], v[46:47], v[78:79]
	v_pk_mul_f32 v[44:45], v[44:45], v[76:77]
	v_pk_mul_f32 v[42:43], v[42:43], v[70:71]
	v_lshl_add_u64 v[32:33], v[32:33], 0, s[44:45]
	v_pk_fma_f32 v[38:39], v[38:39], v[74:75], v[46:47]
	v_pk_fma_f32 v[36:37], v[36:37], v[72:73], v[44:45]
	v_pk_fma_f32 v[42:43], v[34:35], v[66:67], v[42:43]
	v_lshl_add_u64 v[44:45], v[32:33], 0, v[170:171]
	v_cvt_pk_bf16_f32 v32, v50, v51
	v_cvt_pk_bf16_f32 v33, v48, v49
	v_cvt_pk_bf16_f32 v34, v54, v55
	v_cvt_pk_bf16_f32 v35, v52, v53
	v_cvt_pk_bf16_f32 v36, v36, v37
	v_cvt_pk_bf16_f32 v37, v38, v39
	v_cvt_pk_bf16_f32 v38, v40, v41
	v_cvt_pk_bf16_f32 v39, v42, v43
	global_store_dwordx4 v[44:45], v[32:35], off sc1
	global_store_dwordx4 v[44:45], v[36:39], off offset:128 sc1
	v_add_u32_e32 v48, 0x2c00, v208
	v_add_u32_e32 v32, 0x2800, v208
	v_and_b32_e32 v32, 0x7fbc0, v32
	v_lshlrev_b32_e32 v144, 2, v32
	v_lshl_add_u64 v[36:37], v[162:163], 0, v[144:145]
	v_lshl_add_u64 v[44:45], v[164:165], 0, v[144:145]
	global_load_dwordx4 v[32:35], v[36:37], off offset:16
	s_nop 0
	global_load_dwordx4 v[36:39], v[36:37], off
	s_nop 0
	global_load_dwordx4 v[40:43], v[44:45], off offset:16
	s_nop 0
	global_load_dwordx4 v[44:47], v[44:45], off
	v_and_b32_e32 v48, 0x7ffc0, v48
	v_lshlrev_b32_e32 v144, 2, v48
	v_lshl_add_u64 v[52:53], v[162:163], 0, v[144:145]
	v_lshl_add_u64 v[60:61], v[164:165], 0, v[144:145]
	global_load_dwordx4 v[48:51], v[52:53], off offset:16
	s_nop 0
	global_load_dwordx4 v[52:55], v[52:53], off
	s_nop 0
	global_load_dwordx4 v[56:59], v[60:61], off offset:16
	s_nop 0
	global_load_dwordx4 v[60:63], v[60:61], off
	v_mul_f32_e32 v64, v207, v173
	v_pk_mul_f32 v[16:17], v[16:17], v[64:65] op_sel_hi:[1,0]
	v_pk_mul_f32 v[24:25], v[24:25], v[64:65] op_sel_hi:[1,0]
	v_add_u32_e32 v72, 0xa0, v201
	v_pk_mul_f32 v[22:23], v[22:23], v[64:65] op_sel_hi:[1,0]
	v_pk_mul_f32 v[20:21], v[20:21], v[64:65] op_sel_hi:[1,0]
	v_pk_mul_f32 v[18:19], v[18:19], v[64:65] op_sel_hi:[1,0]
	v_pk_mul_f32 v[30:31], v[30:31], v[64:65] op_sel_hi:[1,0]
	v_pk_mul_f32 v[28:29], v[28:29], v[64:65] op_sel_hi:[1,0]
	v_pk_mul_f32 v[26:27], v[26:27], v[64:65] op_sel_hi:[1,0]
	s_waitcnt vmcnt(5)
; __device__ __forceinline__ unsigned pk2(float lo, float hi) { return pg8::cvt_pk_bf16(lo, hi); }
;     __device__ __forceinline__ void operator()(const f32x4 (&acc)[2][2][4][2], const pg8::Unit& u, int wr, int wc, int fr, int fq) const {
;     ...
;             for (int ab = 0; ab < 4; ++ab) { const int ai = ab >> 1, mb = (ab & 1) * 2;
;                 f32x4 cs[4][4];
; #pragma unroll
;                 for (int m = mb; m < mb + 2; ++m) { const int pos = (row0 + ai * 128 + m * 16) & (SEQ - 1); const float* cp = rcos + pos * 64 + dd0; const float* sp = rsin + pos * 64 + dd0;
;                     cs[m][0] = *(const f32x4*)cp; cs[m][1] = *(const f32x4*)(cp + 4); cs[m][2] = *(const f32x4*)sp; cs[m][3] = *(const f32x4*)(sp + 4); }
; #pragma unroll
;                 for (int m = mb; m < mb + 2; ++m) {
;                     const int row = row0 + ai * 128 + m * 16; const float r = rs[ai * 4 + m] * qs;
;                     const f32x4 c0 = cs[m][0], c1 = cs[m][1], s0 = cs[m][2], s1 = cs[m][3];
;                     const f32x4 ta = acc[ai][0][m][0] * r, tb = acc[ai][0][m][1] * r, ua = acc[ai][1][m][0] * r, ub = acc[ai][1][m][1] * r;
;                     const f32x4 o1a = ta * c0 - ua * s0, o1b = tb * c1 - ub * s1, o2a = ta * s0 + ua * c0, o2b = tb * s1 + ub * c1;
;                     bf16* zp = Z + (size_t)row * IW + pn * 256 + hh * 128 + dd0;
;                     u32x4 w1, w2;
;                     w1.x = pk2(o1a.x, o1a.y); w1.y = pk2(o1a.z, o1a.w); w1.z = pk2(o1b.x, o1b.y); w1.w = pk2(o1b.z, o1b.w);
;                     w2.x = pk2(o2a.x, o2a.y); w2.y = pk2(o2a.z, o2a.w); w2.z = pk2(o2b.x, o2b.y); w2.w = pk2(o2b.z, o2b.w);
;                     *(u32x4*)zp = w1; *(u32x4*)(zp + 64) = w2;
;                 }
	v_pk_mul_f32 v[70:71], v[16:17], v[40:41]
	s_nop 0
	v_pk_fma_f32 v[70:71], v[24:25], v[32:33], v[70:71] neg_lo:[0,0,1] neg_hi:[0,0,1]
	v_pk_mul_f32 v[24:25], v[24:25], v[40:41]
	s_waitcnt vmcnt(4)
	v_pk_mul_f32 v[64:65], v[22:23], v[46:47]
	v_pk_fma_f32 v[24:25], v[16:17], v[32:33], v[24:25]
	v_mad_i64_i32 v[16:17], s[0:1], v72, s84, v[112:113]
	v_pk_mul_f32 v[66:67], v[20:21], v[44:45]
	v_pk_mul_f32 v[68:69], v[18:19], v[42:43]
	v_lshl_add_u64 v[16:17], v[16:17], 0, s[82:83]
	v_pk_fma_f32 v[64:65], v[30:31], v[38:39], v[64:65] neg_lo:[0,0,1] neg_hi:[0,0,1]
	v_pk_fma_f32 v[66:67], v[28:29], v[36:37], v[66:67] neg_lo:[0,0,1] neg_hi:[0,0,1]
	v_pk_fma_f32 v[68:69], v[26:27], v[34:35], v[68:69] neg_lo:[0,0,1] neg_hi:[0,0,1]
	v_pk_mul_f32 v[30:31], v[30:31], v[46:47]
	v_pk_mul_f32 v[28:29], v[28:29], v[44:45]
	v_pk_mul_f32 v[26:27], v[26:27], v[42:43]
	v_lshl_add_u64 v[16:17], v[16:17], 0, s[44:45]
	v_pk_fma_f32 v[22:23], v[22:23], v[38:39], v[30:31]
	v_pk_fma_f32 v[20:21], v[20:21], v[36:37], v[28:29]
	v_pk_fma_f32 v[26:27], v[18:19], v[34:35], v[26:27]
	v_lshl_add_u64 v[28:29], v[16:17], 0, v[170:171]
	v_cvt_pk_bf16_f32 v16, v66, v67
	v_cvt_pk_bf16_f32 v17, v64, v65
	v_cvt_pk_bf16_f32 v18, v70, v71
	v_cvt_pk_bf16_f32 v19, v68, v69
	v_cvt_pk_bf16_f32 v20, v20, v21
	v_cvt_pk_bf16_f32 v21, v22, v23
	v_cvt_pk_bf16_f32 v22, v24, v25
	v_cvt_pk_bf16_f32 v23, v26, v27
	global_store_dwordx4 v[28:29], v[16:19], off sc1
	global_store_dwordx4 v[28:29], v[20:23], off offset:128 sc1
	v_add_u32_e32 v24, 0xb0, v201
	v_mul_f32_e32 v16, v207, v172
	v_pk_mul_f32 v[0:1], v[0:1], v[16:17] op_sel_hi:[1,0]
	v_pk_mul_f32 v[8:9], v[8:9], v[16:17] op_sel_hi:[1,0]
	s_waitcnt vmcnt(3)
	v_pk_mul_f32 v[22:23], v[0:1], v[56:57]
	v_pk_mul_f32 v[6:7], v[6:7], v[16:17] op_sel_hi:[1,0]
	v_pk_fma_f32 v[22:23], v[8:9], v[48:49], v[22:23] neg_lo:[0,0,1] neg_hi:[0,0,1]
	v_pk_mul_f32 v[8:9], v[8:9], v[56:57]
	v_pk_mul_f32 v[4:5], v[4:5], v[16:17] op_sel_hi:[1,0]
	v_pk_mul_f32 v[2:3], v[2:3], v[16:17] op_sel_hi:[1,0]
	v_pk_fma_f32 v[8:9], v[0:1], v[48:49], v[8:9]
	v_mad_i64_i32 v[0:1], s[0:1], v24, s84, v[112:113]
	v_pk_mul_f32 v[14:15], v[14:15], v[16:17] op_sel_hi:[1,0]
	v_pk_mul_f32 v[12:13], v[12:13], v[16:17] op_sel_hi:[1,0]
	v_pk_mul_f32 v[10:11], v[10:11], v[16:17] op_sel_hi:[1,0]
	s_waitcnt vmcnt(2)
	v_pk_mul_f32 v[16:17], v[6:7], v[62:63]
	v_pk_mul_f32 v[18:19], v[4:5], v[60:61]
	v_pk_mul_f32 v[20:21], v[2:3], v[58:59]
	v_lshl_add_u64 v[0:1], v[0:1], 0, s[82:83]
	v_pk_fma_f32 v[16:17], v[14:15], v[54:55], v[16:17] neg_lo:[0,0,1] neg_hi:[0,0,1]
	v_pk_fma_f32 v[18:19], v[12:13], v[52:53], v[18:19] neg_lo:[0,0,1] neg_hi:[0,0,1]
	v_pk_fma_f32 v[20:21], v[10:11], v[50:51], v[20:21] neg_lo:[0,0,1] neg_hi:[0,0,1]
	v_pk_mul_f32 v[14:15], v[14:15], v[62:63]
	v_pk_mul_f32 v[12:13], v[12:13], v[60:61]
	v_pk_mul_f32 v[10:11], v[10:11], v[58:59]
	v_lshl_add_u64 v[0:1], v[0:1], 0, s[44:45]
	v_pk_fma_f32 v[6:7], v[6:7], v[54:55], v[14:15]
	v_pk_fma_f32 v[4:5], v[4:5], v[52:53], v[12:13]
	v_pk_fma_f32 v[10:11], v[2:3], v[50:51], v[10:11]
	v_lshl_add_u64 v[12:13], v[0:1], 0, v[170:171]
	v_cvt_pk_bf16_f32 v0, v18, v19
	v_cvt_pk_bf16_f32 v1, v16, v17
	v_cvt_pk_bf16_f32 v2, v22, v23
	v_cvt_pk_bf16_f32 v3, v20, v21
	v_cvt_pk_bf16_f32 v4, v4, v5
	v_cvt_pk_bf16_f32 v5, v6, v7
	v_cvt_pk_bf16_f32 v6, v8, v9
	v_cvt_pk_bf16_f32 v7, v10, v11
	global_store_dwordx4 v[12:13], v[0:3], off sc1
	global_store_dwordx4 v[12:13], v[4:7], off offset:128 sc1
	s_andn2_b64 vcc, exec, s[36:37]
	s_mov_b64 s[0:1], -1
	s_cbranch_vccnz .LBB0_240
	s_branch .LBB0_1022
